# speedup vs baseline: 1.0083x; 1.0027x over previous
; #define WAIT_V(n) asm volatile("s_waitcnt vmcnt(" #n ")" ::: "memory")
; #define BAR __builtin_amdgcn_s_barrier()
; template <int N, int K, int EPI>
; __device__ void gemm_phase(const u16* __restrict__ A, const u16* __restrict__ Bt, const EpiArgs ea, char* smem, int tid) {
;     ...
;   const int wid = __builtin_amdgcn_readfirstlane(tidl >> 6);
;   const int lane = tidl & 63, wr = wid >> 2, wc = wid & 3, fr = lane & 15, fq = lane >> 4;
;   const int tb = tidl * 16;
;   unsigned off0b;
;   { int R, C; stage_rc((tidl & 63) * 16 + wid * 1024, R, C); off0b = (unsigned)(R * K + C) * 2u; }
;   const unsigned lds0 = (unsigned)(size_t)(__attribute__((address_space(3))) char*)smem;
;   int pm, pn; tile_map(v, nN, pm, pn);
;   const u16* Ab = A + (size_t)pm * BM * K;
;   const u16* Bb = Bt + (size_t)pn * BM * K;
;   f32x4 acc[2][2][4][2] = {};
;   bf16x8 At[4][2], B0[2][2], B1[2][2];
;   STAGE(SB(0, 0), GP(Bb, 0, 0)); STAGE(SA(0, 0), GP(Ab, 0, 0));
;   STAGE(SB(0, 1), GP(Bb, 1, 0)); STAGE(SA(0, 1), GP(Ab, 1, 0));
;   if (wr == 1) BAR;
;   WAIT_V(4); BAR;
;   STAGE(SB(1, 0), GP(Bb, 0, 1)); STAGE(SA(1, 0), GP(Ab, 0, 1)); STAGE(SB(1, 1), GP(Bb, 1, 1));
;   WAIT_V(6); BAR;
;   while (true) {
;     const int vn = v + gridDim.x;
;     const bool has_next = vn < nwg;
;     int pmn = pm, pnn = pn;
;     if (has_next) tile_map(vn, nN, pmn, pnn);
.LBB0_60:
	s_and_b32 s20, s2, 3
	s_add_u32 s2, s14, 0x80
	s_addc_u32 s3, s15, 0
	s_add_u32 s4, s14, 0x20080
	s_addc_u32 s5, s15, 0
	s_add_u32 s8, s12, 0x80
	s_addc_u32 s9, s13, 0
	s_add_u32 s10, s12, 0x20080
	s_addc_u32 s11, s13, 0
	s_add_u32 s16, s14, 0x40080
	s_addc_u32 s17, s15, 0
	s_add_u32 s18, s14, 0x60080
	v_readlane_b32 s21, v227, 60
	s_addc_u32 s19, s15, 0
	s_waitcnt vmcnt(2)
	s_barrier
	s_add_i32 s35, s1, s21
	s_mov_b32 m0, s35
	s_nop 0
	global_load_lds_dwordx4 v130, s[2:3]
	v_and_b32_e32 v131, 15, v0
	s_add_i32 s36, s25, 0x1a000
	s_mov_b32 m0, s36
	s_nop 0
	global_load_lds_dwordx4 v130, s[4:5]
	v_lshlrev_b32_e32 v3, 2, v0
	v_lshrrev_b32_e32 v132, 4, v1
	s_add_i32 s37, s25, 0x8000
	s_mov_b32 m0, s37
	s_nop 0
	global_load_lds_dwordx4 v130, s[8:9]
	v_and_b32_e32 v1, 48, v0
	v_lshlrev_b32_e32 v2, 6, v131
	v_and_b32_e32 v3, 32, v3
	s_add_i32 s42, s25, 0xa000
	s_mov_b32 m0, s42
	s_nop 0
	global_load_lds_dwordx4 v130, s[10:11]
	v_readlane_b32 s3, v227, 61
	v_bitop3_b32 v2, v2, v3, v1 bitop3:0x36
	s_add_i32 s2, 0, 0x10000
	s_add_i32 s43, s1, s3
	s_mov_b32 m0, s43
	s_nop 0
	global_load_lds_dwordx4 v130, s[16:17]
	v_add_u32_e32 v4, s2, v2
	s_add_i32 s2, 0, 0x14000
	s_add_i32 s66, s25, 0x1e000
	s_mov_b32 m0, s66
	s_nop 0
	global_load_lds_dwordx4 v130, s[18:19]
	v_add_u32_e32 v5, s2, v2
	v_lshlrev_b32_e32 v0, 6, v0
	s_movk_i32 s2, 0x3c0
	s_waitcnt vmcnt(6)
	s_lshl_b32 s1, s20, 12
	s_lshl_b32 s67, s0, 6
	v_add_u32_e32 v6, s21, v2
	v_add_u32_e32 v7, s3, v2
	s_lshl_b32 s0, s0, 13
	v_add_u32_e32 v2, 0, v2
	v_and_or_b32 v0, v0, s2, v1
	v_xad_u32 v134, v0, v3, 0
	s_or_b32 s89, s0, 0x800
	s_or_b32 s2, s0, 0x1000
	s_or_b32 s3, s0, 0x1800
	v_add_u32_e32 v135, s1, v4
	v_add_u32_e32 v136, s0, v2
	v_add_u32_e32 v139, s1, v5
	v_add_u32_e32 v140, s1, v6
	v_add_u32_e32 v141, s1, v7
	v_readlane_b32 s0, v227, 9
	s_add_i32 s72, s25, 0xc000
	s_add_i32 s73, s25, 0xe000
	s_lshl_b32 s88, s20, 5
	v_add_u32_e32 v137, s2, v134
	v_add_u32_e32 v138, s3, v134
	s_mov_b32 s24, s0
	v_readlane_b32 s95, v227, 8
	v_readlane_b32 s94, v226, 8
	s_barrier
	v_readlane_b32 s1, v227, 10
	v_and_b32_e32 v120, 15, v164
	v_bfe_u32 v121, v164, 4, 2
	v_lshrrev_b32_e32 v122, 3, v120
	v_and_b32_e32 v123, 7, v120
	v_lshlrev_b32_e32 v124, 10, v122
	v_lshl_add_u32 v124, v123, 7, v124
	v_lshl_add_u32 v124, v122, 6, v124
	v_bfe_u32 v125, v120, 1, 2
	v_xor_b32_e32 v125, v125, v121
	v_lshl_add_u32 v124, v125, 4, v124
	v_lshrrev_b32_e32 v126, 8, v164
	v_lshl_add_u32 v136, v126, 13, v124
	v_xor_b32_e32 v137, 64, v136
	v_bfe_u32 v126, v164, 6, 2
	v_lshl_add_u32 v126, v126, 12, v124
	v_add_u32_e32 v135, 0x10000, v126
	v_xor_b32_e32 v139, 64, v135
	v_readfirstlane_b32 s100, v164
	s_lshr_b32 s100, s100, 8
	s_cmp_eq_u32 s100, 1
	s_cbranch_scc0 .Lsp_wout
	s_setprio 1
.Lsp_wout:
.LBB0_61:
	s_add_i32 s94, s94, s33
	s_cmpk_gt_i32 s94, 0x1ff
	s_cselect_b64 s[0:1], -1, 0
	s_and_b64 vcc, exec, s[0:1]
	s_mov_b32 s2, s24
	s_mov_b32 s4, s95
	s_cbranch_vccnz .LBB0_63
	s_lshl_b32 s3, s94, 6
	s_ashr_i32 s2, s94, 3
	s_and_b32 s3, s3, 0x1c0
	s_add_i32 s2, s3, s2
	s_ashr_i32 s3, s2, 31
	s_lshr_b32 s3, s3, 27
	s_add_i32 s3, s2, s3
	s_ashr_i32 s4, s3, 5
	s_and_b32 s3, s3, 0xffe0
	s_sub_i32 s2, s2, s3
	s_bfe_i32 s3, s2, 0x80000
	s_bfe_u32 s3, s3, 0x3000c
	s_add_i32 s3, s2, s3
	s_bfe_i32 s5, s3, 0x80000
	s_and_b32 s3, s3, 0xf8
	s_sub_i32 s2, s2, s3
	s_lshl_b32 s4, s4, 3
	s_sext_i32_i16 s5, s5
	s_sext_i32_i8 s2, s2
	s_add_i32 s2, s4, s2
	s_ashr_i32 s4, s5, 3

.LBB0_64:
	ds_read_b128 v[142:145], v135
	ds_read_b128 v[166:169], v139
	ds_read_b128 v[170:173], v135 offset:2048
	ds_read_b128 v[174:177], v139 offset:2048
	s_add_u32 s18, s16, 0x40080
	s_addc_u32 s19, s17, 0
	s_add_u32 s20, s16, 0x60080
	s_addc_u32 s21, s17, 0
	s_cmp_eq_u32 s3, 12
	s_cselect_b32 vcc_lo, s11, s15
	s_cselect_b32 vcc_hi, s10, s14
	s_cselect_b32 s82, s9, s13
	s_cselect_b32 s83, s8, s12
	s_nop 0
	ds_read_b128 v[178:181], v136
	ds_read_b128 v[182:185], v137
	ds_read_b128 v[186:189], v136 offset:2048
	ds_read_b128 v[190:193], v137 offset:2048
	ds_read_b128 v[194:197], v136 offset:4096
	ds_read_b128 v[198:201], v137 offset:4096
	ds_read_b128 v[202:205], v136 offset:6144
	ds_read_b128 v[206:209], v137 offset:6144
	s_mov_b32 m0, s72
	s_nop 0
	global_load_lds_dwordx4 v130, s[18:19]
	s_nop 0
	s_mov_b32 m0, s73
	s_nop 0
	global_load_lds_dwordx4 v130, s[20:21]
	ds_read_b128 v[210:213], v135 offset:16384
	ds_read_b128 v[214:217], v139 offset:16384
	ds_read_b128 v[218:221], v135 offset:18432
	ds_read_b128 v[222:225], v139 offset:18432
	s_waitcnt vmcnt(8) lgkmcnt(0)
	s_barrier
	s_waitcnt lgkmcnt(7)
	v_mfma_f32_16x16x32_bf16 v[124:127], v[142:145], v[178:181], v[124:127]
	v_mfma_f32_16x16x32_bf16 v[120:123], v[170:173], v[178:181], v[120:123]
	s_waitcnt lgkmcnt(5)
	v_mfma_f32_16x16x32_bf16 v[116:119], v[142:145], v[186:189], v[116:119]
	v_mfma_f32_16x16x32_bf16 v[112:115], v[170:173], v[186:189], v[112:115]
	s_waitcnt lgkmcnt(3)
	v_mfma_f32_16x16x32_bf16 v[108:111], v[142:145], v[194:197], v[108:111]
	v_mfma_f32_16x16x32_bf16 v[104:107], v[170:173], v[194:197], v[104:107]
	s_waitcnt lgkmcnt(1)
	v_mfma_f32_16x16x32_bf16 v[100:103], v[142:145], v[202:205], v[100:103]
	v_mfma_f32_16x16x32_bf16 v[96:99], v[170:173], v[202:205], v[96:99]
	v_mfma_f32_16x16x32_bf16 v[124:127], v[166:169], v[182:185], v[124:127]
	v_mfma_f32_16x16x32_bf16 v[120:123], v[174:177], v[182:185], v[120:123]
	v_mfma_f32_16x16x32_bf16 v[116:119], v[166:169], v[190:193], v[116:119]
	v_mfma_f32_16x16x32_bf16 v[112:115], v[174:177], v[190:193], v[112:115]
	v_mfma_f32_16x16x32_bf16 v[108:111], v[166:169], v[198:201], v[108:111]
	v_mfma_f32_16x16x32_bf16 v[104:107], v[174:177], v[198:201], v[104:107]
	s_waitcnt lgkmcnt(0)
	v_mfma_f32_16x16x32_bf16 v[100:103], v[166:169], v[206:209], v[100:103]
	v_mfma_f32_16x16x32_bf16 v[96:99], v[174:177], v[206:209], v[96:99]
	s_waitcnt lgkmcnt(3)
	v_mfma_f32_16x16x32_bf16 v[92:95], v[210:213], v[178:181], v[92:95]
	s_waitcnt lgkmcnt(1)
	v_mfma_f32_16x16x32_bf16 v[88:91], v[218:221], v[178:181], v[88:91]
	v_mfma_f32_16x16x32_bf16 v[84:87], v[210:213], v[186:189], v[84:87]
	v_mfma_f32_16x16x32_bf16 v[80:83], v[218:221], v[186:189], v[80:83]
	v_mfma_f32_16x16x32_bf16 v[76:79], v[210:213], v[194:197], v[76:79]
	v_mfma_f32_16x16x32_bf16 v[72:75], v[218:221], v[194:197], v[72:75]
	v_mfma_f32_16x16x32_bf16 v[68:71], v[210:213], v[202:205], v[68:71]
	v_mfma_f32_16x16x32_bf16 v[64:67], v[218:221], v[202:205], v[64:67]
	v_mfma_f32_16x16x32_bf16 v[92:95], v[214:217], v[182:185], v[92:95]
	s_waitcnt lgkmcnt(0)
	v_mfma_f32_16x16x32_bf16 v[88:91], v[222:225], v[182:185], v[88:91]
	v_mfma_f32_16x16x32_bf16 v[84:87], v[214:217], v[190:193], v[84:87]
	v_mfma_f32_16x16x32_bf16 v[80:83], v[222:225], v[190:193], v[80:83]
	v_mfma_f32_16x16x32_bf16 v[76:79], v[214:217], v[198:201], v[76:79]
	v_mfma_f32_16x16x32_bf16 v[72:75], v[222:225], v[198:201], v[72:75]
	v_mfma_f32_16x16x32_bf16 v[68:71], v[214:217], v[206:209], v[68:71]
	v_mfma_f32_16x16x32_bf16 v[64:67], v[222:225], v[206:209], v[64:67]
	s_barrier
	s_cselect_b32 s70, 0, s5
	s_lshl_b64 s[92:93], s[70:71], 1
	s_add_u32 s18, vcc_hi, s92
	s_addc_u32 s19, vcc_lo, s93
	s_add_u32 s20, s18, 0x20000
	s_mov_b32 m0, s26
	s_nop 0
	global_load_lds_dwordx4 v130, s[18:19]
	s_addc_u32 s21, s19, 0
	s_mov_b32 m0, s27
	s_nop 0
	global_load_lds_dwordx4 v130, s[20:21]
	ds_read_b128 v[178:181], v136 offset:16384
	ds_read_b128 v[182:185], v137 offset:16384
	ds_read_b128 v[186:189], v136 offset:18432
	ds_read_b128 v[190:193], v137 offset:18432
	ds_read_b128 v[194:197], v136 offset:20480
	ds_read_b128 v[198:201], v137 offset:20480
	ds_read_b128 v[202:205], v136 offset:22528
	ds_read_b128 v[206:209], v137 offset:22528
	s_add_u32 s20, s83, s92
	s_addc_u32 s21, s82, s93
	s_add_u32 s82, s20, 0x20000
	s_mov_b32 m0, s25
	s_nop 0
	global_load_lds_dwordx4 v130, s[20:21]
	s_addc_u32 s83, s21, 0
	s_mov_b32 m0, s28
	s_nop 0
	global_load_lds_dwordx4 v130, s[82:83]
	s_add_u32 vcc_hi, vcc_hi, 0x40000
	s_addc_u32 vcc_lo, vcc_lo, 0
	s_add_u32 s82, vcc_hi, s92
	s_addc_u32 s83, vcc_lo, s93
	s_add_u32 s92, s82, 0x20000
	s_mov_b32 m0, s29
	s_nop 0
	global_load_lds_dwordx4 v130, s[82:83]
	s_addc_u32 s93, s83, 0
	s_mov_b32 m0, s30
	s_nop 0
	global_load_lds_dwordx4 v130, s[92:93]
	s_waitcnt vmcnt(8) lgkmcnt(0)
	s_barrier
	s_waitcnt lgkmcnt(7)
	v_mfma_f32_16x16x32_bf16 v[60:63], v[142:145], v[178:181], v[60:63]
	v_mfma_f32_16x16x32_bf16 v[56:59], v[170:173], v[178:181], v[56:59]
	s_waitcnt lgkmcnt(5)
	v_mfma_f32_16x16x32_bf16 v[52:55], v[142:145], v[186:189], v[52:55]
	v_mfma_f32_16x16x32_bf16 v[48:51], v[170:173], v[186:189], v[48:51]
	s_waitcnt lgkmcnt(3)
	v_mfma_f32_16x16x32_bf16 v[44:47], v[142:145], v[194:197], v[44:47]
	v_mfma_f32_16x16x32_bf16 v[40:43], v[170:173], v[194:197], v[40:43]
	s_waitcnt lgkmcnt(1)
	v_mfma_f32_16x16x32_bf16 v[36:39], v[142:145], v[202:205], v[36:39]
	v_mfma_f32_16x16x32_bf16 v[32:35], v[170:173], v[202:205], v[32:35]
	v_mfma_f32_16x16x32_bf16 v[60:63], v[166:169], v[182:185], v[60:63]
	v_mfma_f32_16x16x32_bf16 v[56:59], v[174:177], v[182:185], v[56:59]
	v_mfma_f32_16x16x32_bf16 v[52:55], v[166:169], v[190:193], v[52:55]
	v_mfma_f32_16x16x32_bf16 v[48:51], v[174:177], v[190:193], v[48:51]
	v_mfma_f32_16x16x32_bf16 v[44:47], v[166:169], v[198:201], v[44:47]
	v_mfma_f32_16x16x32_bf16 v[40:43], v[174:177], v[198:201], v[40:43]
	s_waitcnt lgkmcnt(0)
	v_mfma_f32_16x16x32_bf16 v[36:39], v[166:169], v[206:209], v[36:39]
	v_mfma_f32_16x16x32_bf16 v[32:35], v[174:177], v[206:209], v[32:35]
	v_mfma_f32_16x16x32_bf16 v[28:31], v[210:213], v[178:181], v[28:31]
	v_mfma_f32_16x16x32_bf16 v[24:27], v[218:221], v[178:181], v[24:27]
	v_mfma_f32_16x16x32_bf16 v[20:23], v[210:213], v[186:189], v[20:23]
	v_mfma_f32_16x16x32_bf16 v[16:19], v[218:221], v[186:189], v[16:19]
	v_mfma_f32_16x16x32_bf16 v[12:15], v[210:213], v[194:197], v[12:15]
	v_mfma_f32_16x16x32_bf16 v[8:11], v[218:221], v[194:197], v[8:11]
	v_mfma_f32_16x16x32_bf16 v[4:7], v[210:213], v[202:205], v[4:7]
	v_mfma_f32_16x16x32_bf16 v[0:3], v[218:221], v[202:205], v[0:3]
	v_mfma_f32_16x16x32_bf16 v[28:31], v[214:217], v[182:185], v[28:31]
	v_mfma_f32_16x16x32_bf16 v[24:27], v[222:225], v[182:185], v[24:27]
	v_mfma_f32_16x16x32_bf16 v[20:23], v[214:217], v[190:193], v[20:23]
	v_mfma_f32_16x16x32_bf16 v[16:19], v[222:225], v[190:193], v[16:19]
	v_mfma_f32_16x16x32_bf16 v[12:15], v[214:217], v[198:201], v[12:15]
	v_mfma_f32_16x16x32_bf16 v[8:11], v[222:225], v[198:201], v[8:11]
	v_mfma_f32_16x16x32_bf16 v[4:7], v[214:217], v[206:209], v[4:7]
	v_mfma_f32_16x16x32_bf16 v[0:3], v[222:225], v[206:209], v[0:3]
	s_barrier
	ds_read_b128 v[142:145], v135 offset:32768
	ds_read_b128 v[166:169], v139 offset:32768
	ds_read_b128 v[170:173], v135 offset:34816
	ds_read_b128 v[174:177], v139 offset:34816
	ds_read_b128 v[178:181], v136 offset:32768
	ds_read_b128 v[182:185], v137 offset:32768
	ds_read_b128 v[186:189], v136 offset:34816
	ds_read_b128 v[190:193], v137 offset:34816
	ds_read_b128 v[194:197], v136 offset:36864
	ds_read_b128 v[198:201], v137 offset:36864
	ds_read_b128 v[202:205], v136 offset:38912
	ds_read_b128 v[206:209], v137 offset:38912
	s_add_u32 s82, s20, 0x40000
	s_addc_u32 s83, s21, 0
	s_add_u32 s92, s20, 0x60000
	s_mov_b32 m0, s31
	s_nop 0
	global_load_lds_dwordx4 v130, s[82:83]
	s_addc_u32 s93, s21, 0
	s_mov_b32 m0, s34
	s_nop 0
	global_load_lds_dwordx4 v130, s[92:93]
	ds_read_b128 v[210:213], v135 offset:49152
	ds_read_b128 v[214:217], v139 offset:49152
	ds_read_b128 v[218:221], v135 offset:51200
	ds_read_b128 v[222:225], v139 offset:51200
	s_waitcnt vmcnt(8) lgkmcnt(0)
	s_barrier
	s_waitcnt lgkmcnt(7)
	v_mfma_f32_16x16x32_bf16 v[124:127], v[142:145], v[178:181], v[124:127]
	v_mfma_f32_16x16x32_bf16 v[120:123], v[170:173], v[178:181], v[120:123]
	s_waitcnt lgkmcnt(5)
	v_mfma_f32_16x16x32_bf16 v[116:119], v[142:145], v[186:189], v[116:119]
	v_mfma_f32_16x16x32_bf16 v[112:115], v[170:173], v[186:189], v[112:115]
	s_waitcnt lgkmcnt(3)
	v_mfma_f32_16x16x32_bf16 v[108:111], v[142:145], v[194:197], v[108:111]
	v_mfma_f32_16x16x32_bf16 v[104:107], v[170:173], v[194:197], v[104:107]
	s_waitcnt lgkmcnt(1)
	v_mfma_f32_16x16x32_bf16 v[100:103], v[142:145], v[202:205], v[100:103]
	v_mfma_f32_16x16x32_bf16 v[96:99], v[170:173], v[202:205], v[96:99]
	v_mfma_f32_16x16x32_bf16 v[124:127], v[166:169], v[182:185], v[124:127]
	v_mfma_f32_16x16x32_bf16 v[120:123], v[174:177], v[182:185], v[120:123]
	v_mfma_f32_16x16x32_bf16 v[116:119], v[166:169], v[190:193], v[116:119]
	v_mfma_f32_16x16x32_bf16 v[112:115], v[174:177], v[190:193], v[112:115]
	v_mfma_f32_16x16x32_bf16 v[108:111], v[166:169], v[198:201], v[108:111]
	v_mfma_f32_16x16x32_bf16 v[104:107], v[174:177], v[198:201], v[104:107]
	s_waitcnt lgkmcnt(0)
	v_mfma_f32_16x16x32_bf16 v[100:103], v[166:169], v[206:209], v[100:103]
	v_mfma_f32_16x16x32_bf16 v[96:99], v[174:177], v[206:209], v[96:99]
	s_waitcnt lgkmcnt(3)
	v_mfma_f32_16x16x32_bf16 v[92:95], v[210:213], v[178:181], v[92:95]
	s_waitcnt lgkmcnt(1)
	v_mfma_f32_16x16x32_bf16 v[88:91], v[218:221], v[178:181], v[88:91]
	v_mfma_f32_16x16x32_bf16 v[84:87], v[210:213], v[186:189], v[84:87]
	v_mfma_f32_16x16x32_bf16 v[80:83], v[218:221], v[186:189], v[80:83]
	v_mfma_f32_16x16x32_bf16 v[76:79], v[210:213], v[194:197], v[76:79]
	v_mfma_f32_16x16x32_bf16 v[72:75], v[218:221], v[194:197], v[72:75]
	v_mfma_f32_16x16x32_bf16 v[68:71], v[210:213], v[202:205], v[68:71]
	v_mfma_f32_16x16x32_bf16 v[64:67], v[218:221], v[202:205], v[64:67]
	v_mfma_f32_16x16x32_bf16 v[92:95], v[214:217], v[182:185], v[92:95]
	s_waitcnt lgkmcnt(0)
	v_mfma_f32_16x16x32_bf16 v[88:91], v[222:225], v[182:185], v[88:91]
	v_mfma_f32_16x16x32_bf16 v[84:87], v[214:217], v[190:193], v[84:87]
	v_mfma_f32_16x16x32_bf16 v[80:83], v[222:225], v[190:193], v[80:83]
	v_mfma_f32_16x16x32_bf16 v[76:79], v[214:217], v[198:201], v[76:79]
	v_mfma_f32_16x16x32_bf16 v[72:75], v[222:225], v[198:201], v[72:75]
	v_mfma_f32_16x16x32_bf16 v[68:71], v[214:217], v[206:209], v[68:71]
	v_mfma_f32_16x16x32_bf16 v[64:67], v[222:225], v[206:209], v[64:67]
	s_barrier
	s_or_b32 s70, s70, 64
	s_add_u32 s82, s18, 0x80
	s_addc_u32 s83, s19, 0
	s_add_u32 s18, s18, 0x20080
	s_mov_b32 m0, s35
	s_nop 0
	global_load_lds_dwordx4 v130, s[82:83]
	s_addc_u32 s19, s19, 0
	s_mov_b32 m0, s36
	s_nop 0
	global_load_lds_dwordx4 v130, s[18:19]
	ds_read_b128 v[178:181], v136 offset:49152
	ds_read_b128 v[182:185], v137 offset:49152
	ds_read_b128 v[186:189], v136 offset:51200
	ds_read_b128 v[190:193], v137 offset:51200
	ds_read_b128 v[194:197], v136 offset:53248
	ds_read_b128 v[198:201], v137 offset:53248
	ds_read_b128 v[202:205], v136 offset:55296
	ds_read_b128 v[206:209], v137 offset:55296
	s_add_u32 s18, s20, 0x80
	s_addc_u32 s19, s21, 0
	s_add_u32 s20, s20, 0x20080
	s_mov_b32 m0, s37
	s_nop 0
	global_load_lds_dwordx4 v130, s[18:19]
	s_addc_u32 s21, s21, 0
	s_mov_b32 m0, s42
	s_nop 0
	global_load_lds_dwordx4 v130, s[20:21]
	s_lshl_b64 s[18:19], s[70:71], 1
	s_add_u32 s18, vcc_hi, s18
	s_addc_u32 s19, vcc_lo, s19
	s_add_u32 s20, s18, 0x20000
	s_mov_b32 m0, s43
	s_nop 0
	global_load_lds_dwordx4 v130, s[18:19]
	s_addc_u32 s21, s19, 0
	s_mov_b32 m0, s66
	s_nop 0
	global_load_lds_dwordx4 v130, s[20:21]
	s_waitcnt vmcnt(8) lgkmcnt(0)
	s_barrier
	s_waitcnt lgkmcnt(7)
	v_mfma_f32_16x16x32_bf16 v[60:63], v[142:145], v[178:181], v[60:63]
	v_mfma_f32_16x16x32_bf16 v[56:59], v[170:173], v[178:181], v[56:59]
	s_waitcnt lgkmcnt(5)
	v_mfma_f32_16x16x32_bf16 v[52:55], v[142:145], v[186:189], v[52:55]
	v_mfma_f32_16x16x32_bf16 v[48:51], v[170:173], v[186:189], v[48:51]
	s_waitcnt lgkmcnt(3)
	v_mfma_f32_16x16x32_bf16 v[44:47], v[142:145], v[194:197], v[44:47]
	v_mfma_f32_16x16x32_bf16 v[40:43], v[170:173], v[194:197], v[40:43]
	s_waitcnt lgkmcnt(1)
	v_mfma_f32_16x16x32_bf16 v[36:39], v[142:145], v[202:205], v[36:39]
	v_mfma_f32_16x16x32_bf16 v[32:35], v[170:173], v[202:205], v[32:35]
	v_mfma_f32_16x16x32_bf16 v[60:63], v[166:169], v[182:185], v[60:63]
	v_mfma_f32_16x16x32_bf16 v[56:59], v[174:177], v[182:185], v[56:59]
	v_mfma_f32_16x16x32_bf16 v[52:55], v[166:169], v[190:193], v[52:55]
	v_mfma_f32_16x16x32_bf16 v[48:51], v[174:177], v[190:193], v[48:51]
	v_mfma_f32_16x16x32_bf16 v[44:47], v[166:169], v[198:201], v[44:47]
	v_mfma_f32_16x16x32_bf16 v[40:43], v[174:177], v[198:201], v[40:43]
	s_waitcnt lgkmcnt(0)
	v_mfma_f32_16x16x32_bf16 v[36:39], v[166:169], v[206:209], v[36:39]
	v_mfma_f32_16x16x32_bf16 v[32:35], v[174:177], v[206:209], v[32:35]
	v_mfma_f32_16x16x32_bf16 v[28:31], v[210:213], v[178:181], v[28:31]
	v_mfma_f32_16x16x32_bf16 v[24:27], v[218:221], v[178:181], v[24:27]
	v_mfma_f32_16x16x32_bf16 v[20:23], v[210:213], v[186:189], v[20:23]
	v_mfma_f32_16x16x32_bf16 v[16:19], v[218:221], v[186:189], v[16:19]
	v_mfma_f32_16x16x32_bf16 v[12:15], v[210:213], v[194:197], v[12:15]
	v_mfma_f32_16x16x32_bf16 v[8:11], v[218:221], v[194:197], v[8:11]
	v_mfma_f32_16x16x32_bf16 v[4:7], v[210:213], v[202:205], v[4:7]
	v_mfma_f32_16x16x32_bf16 v[0:3], v[218:221], v[202:205], v[0:3]
	v_mfma_f32_16x16x32_bf16 v[28:31], v[214:217], v[182:185], v[28:31]
	v_mfma_f32_16x16x32_bf16 v[24:27], v[222:225], v[182:185], v[24:27]
	v_mfma_f32_16x16x32_bf16 v[20:23], v[214:217], v[190:193], v[20:23]
	v_mfma_f32_16x16x32_bf16 v[16:19], v[222:225], v[190:193], v[16:19]
	v_mfma_f32_16x16x32_bf16 v[12:15], v[214:217], v[198:201], v[12:15]
	v_mfma_f32_16x16x32_bf16 v[8:11], v[222:225], v[198:201], v[8:11]
	v_mfma_f32_16x16x32_bf16 v[4:7], v[214:217], v[206:209], v[4:7]
	v_mfma_f32_16x16x32_bf16 v[0:3], v[222:225], v[206:209], v[0:3]
	s_add_i32 s3, s3, 2
	s_addk_i32 s5, 0x80
	s_add_u32 s16, s16, 0x100
	s_addc_u32 s17, s17, 0
	s_cmp_gt_u32 s3, 13
	s_barrier
	s_cbranch_scc0 .LBB0_64
; #define WAIT_V(n) asm volatile("s_waitcnt vmcnt(" #n ")" ::: "memory")
; #define BAR __builtin_amdgcn_s_barrier()
; template <int N, int K, int EPI>
; __device__ void gemm_phase(const u16* __restrict__ A, const u16* __restrict__ Bt, const EpiArgs ea, char* smem, int tid) {
;     ...
;         u16* f = ea.o0;
; #pragma unroll
;         for (int ai = 0; ai < 2; ++ai)
; #pragma unroll
;           for (int bj = 0; bj < 2; ++bj)
; #pragma unroll
;             for (int m = 0; m < 4; ++m) {
;               const int row = brow + ai * HALF + wr * 64 + m * 16 + fr_e;
;               const int col = pn * BM + bj * HALF + wc * 32 + fq_e * 8;
;               const f32x4 v0 = acc[ai][bj][m][0], v1 = acc[ai][bj][m][1];
;               u32x4 o = {pk_bf16(v0[0], v0[1]), pk_bf16(v0[2], v0[3]), pk_bf16(v1[0], v1[1]), pk_bf16(v1[2], v1[3])};
;               *(u32x4*)(f + (size_t)row * N + col) = o;
;             }
;     ...
;     if (!has_next) break;
; #pragma unroll
;     for (int ai = 0; ai < 2; ++ai)
; #pragma unroll
;       for (int bj = 0; bj < 2; ++bj)
; #pragma unroll
;         for (int m = 0; m < 4; ++m)
; #pragma unroll
;           for (int n = 0; n < 2; ++n) acc[ai][bj][m][n] = f32x4{0.f, 0.f, 0.f, 0.f};
;     v = vn; pm = pmn; pn = pnn; Ab = Abn; Bb = Bbn;
;   }
;   WAIT_V(0);
;   if (wr == 0) BAR;
	s_lshl_b32 s3, s24, 8
	v_mov_b32_e32 v128, v131
	v_mov_b32_e32 v129, v132
	s_add_i32 s3, s3, s67
	v_cvt_pk_bf16_f32 v124, v124, v125
	v_cvt_pk_bf16_f32 v125, v126, v127
	v_cvt_pk_bf16_f32 v126, v120, v121
	v_cvt_pk_bf16_f32 v127, v122, v123
	v_cvt_pk_bf16_f32 v116, v116, v117
	s_nop 0
	v_add_u32_e32 v142, s3, v128
	s_lshl_b32 s3, s95, 8
	s_or_b32 s3, s3, s88
	v_lshl_add_u32 v144, v129, 3, s3
	v_ashrrev_i32_e32 v145, 31, v144
	v_ashrrev_i32_e32 v143, 31, v142
	v_lshl_add_u64 v[128:129], v[144:145], 1, s[64:65]
	v_lshlrev_b64 v[120:121], 11, v[142:143]
	v_lshl_add_u64 v[122:123], v[128:129], 0, v[120:121]
	global_store_dwordx4 v[122:123], v[124:127], off
	v_add_u32_e32 v122, 16, v142
	v_ashrrev_i32_e32 v123, 31, v122
	v_cvt_pk_bf16_f32 v117, v118, v119
	v_cvt_pk_bf16_f32 v118, v112, v113
	v_lshlrev_b64 v[112:113], 11, v[122:123]
	v_cvt_pk_bf16_f32 v119, v114, v115
	v_lshl_add_u64 v[114:115], v[128:129], 0, v[112:113]
	global_store_dwordx4 v[114:115], v[116:119], off
	v_add_u32_e32 v114, 32, v142
	v_ashrrev_i32_e32 v115, 31, v114
	v_cvt_pk_bf16_f32 v108, v108, v109
	v_cvt_pk_bf16_f32 v109, v110, v111
	v_cvt_pk_bf16_f32 v110, v104, v105
	v_lshlrev_b64 v[104:105], 11, v[114:115]
	v_cvt_pk_bf16_f32 v111, v106, v107
	v_lshl_add_u64 v[106:107], v[128:129], 0, v[104:105]
	global_store_dwordx4 v[106:107], v[108:111], off
	v_add_u32_e32 v106, 48, v142
	v_ashrrev_i32_e32 v107, 31, v106
	v_cvt_pk_bf16_f32 v100, v100, v101
	v_cvt_pk_bf16_f32 v101, v102, v103
	v_cvt_pk_bf16_f32 v102, v96, v97
	v_lshlrev_b64 v[96:97], 11, v[106:107]
	v_cvt_pk_bf16_f32 v103, v98, v99
	v_lshl_add_u64 v[98:99], v[128:129], 0, v[96:97]
	global_store_dwordx4 v[98:99], v[100:103], off
	v_add_u32_e32 v98, 0x80, v144
	v_ashrrev_i32_e32 v99, 31, v98
	v_lshl_add_u64 v[98:99], v[98:99], 1, s[64:65]
	v_cvt_pk_bf16_f32 v68, v68, v69
	v_cvt_pk_bf16_f32 v69, v70, v71
	v_cvt_pk_bf16_f32 v70, v64, v65
	v_lshl_add_u64 v[64:65], v[98:99], 0, v[96:97]
	v_cvt_pk_bf16_f32 v71, v66, v67
	global_store_dwordx4 v[64:65], v[68:71], off
	v_add_u32_e32 v64, 0x80, v142
	v_ashrrev_i32_e32 v65, 31, v64
	v_cvt_pk_bf16_f32 v60, v60, v61
	v_cvt_pk_bf16_f32 v61, v62, v63
	v_cvt_pk_bf16_f32 v62, v56, v57
	v_lshlrev_b64 v[56:57], 11, v[64:65]
	v_cvt_pk_bf16_f32 v92, v92, v93
	v_cvt_pk_bf16_f32 v93, v94, v95
	v_cvt_pk_bf16_f32 v94, v88, v89
	v_lshl_add_u64 v[88:89], v[98:99], 0, v[120:121]
	v_cvt_pk_bf16_f32 v84, v84, v85
	v_cvt_pk_bf16_f32 v85, v86, v87
	v_cvt_pk_bf16_f32 v86, v80, v81
	v_lshl_add_u64 v[80:81], v[98:99], 0, v[112:113]
	v_cvt_pk_bf16_f32 v76, v76, v77
	v_cvt_pk_bf16_f32 v77, v78, v79
	v_cvt_pk_bf16_f32 v78, v72, v73
	v_lshl_add_u64 v[72:73], v[98:99], 0, v[104:105]
	v_cvt_pk_bf16_f32 v63, v58, v59
	v_lshl_add_u64 v[58:59], v[128:129], 0, v[56:57]
	v_cvt_pk_bf16_f32 v95, v90, v91
	global_store_dwordx4 v[88:89], v[92:95], off
	v_cvt_pk_bf16_f32 v87, v82, v83
	global_store_dwordx4 v[80:81], v[84:87], off
	v_cvt_pk_bf16_f32 v79, v74, v75
	global_store_dwordx4 v[72:73], v[76:79], off
	global_store_dwordx4 v[58:59], v[60:63], off
	v_add_u32_e32 v58, 0x90, v142
	v_ashrrev_i32_e32 v59, 31, v58
	v_cvt_pk_bf16_f32 v52, v52, v53
	v_cvt_pk_bf16_f32 v53, v54, v55
	v_cvt_pk_bf16_f32 v54, v48, v49
	v_lshlrev_b64 v[48:49], 11, v[58:59]
	v_cvt_pk_bf16_f32 v55, v50, v51
	v_lshl_add_u64 v[50:51], v[128:129], 0, v[48:49]
	global_store_dwordx4 v[50:51], v[52:55], off
	v_add_u32_e32 v50, 0xa0, v142
	v_ashrrev_i32_e32 v51, 31, v50
	v_cvt_pk_bf16_f32 v44, v44, v45
	v_cvt_pk_bf16_f32 v45, v46, v47
	v_cvt_pk_bf16_f32 v46, v40, v41
	v_lshlrev_b64 v[40:41], 11, v[50:51]
	v_cvt_pk_bf16_f32 v47, v42, v43
	v_lshl_add_u64 v[42:43], v[128:129], 0, v[40:41]
	global_store_dwordx4 v[42:43], v[44:47], off
	v_add_u32_e32 v42, 0xb0, v142
	v_ashrrev_i32_e32 v43, 31, v42
	v_cvt_pk_bf16_f32 v36, v36, v37
	v_cvt_pk_bf16_f32 v37, v38, v39
	v_cvt_pk_bf16_f32 v38, v32, v33
	v_lshlrev_b64 v[32:33], 11, v[42:43]
	v_cvt_pk_bf16_f32 v39, v34, v35
	v_lshl_add_u64 v[34:35], v[128:129], 0, v[32:33]
	v_cvt_pk_bf16_f32 v28, v28, v29
	v_cvt_pk_bf16_f32 v29, v30, v31
	v_cvt_pk_bf16_f32 v30, v24, v25
	v_lshl_add_u64 v[24:25], v[98:99], 0, v[56:57]
	v_cvt_pk_bf16_f32 v20, v20, v21
	v_cvt_pk_bf16_f32 v21, v22, v23
	v_cvt_pk_bf16_f32 v22, v16, v17
	v_lshl_add_u64 v[16:17], v[98:99], 0, v[48:49]
	v_cvt_pk_bf16_f32 v12, v12, v13
	v_cvt_pk_bf16_f32 v13, v14, v15
	v_cvt_pk_bf16_f32 v14, v8, v9
	v_lshl_add_u64 v[8:9], v[98:99], 0, v[40:41]
	v_cvt_pk_bf16_f32 v4, v4, v5
	v_cvt_pk_bf16_f32 v5, v6, v7
	v_cvt_pk_bf16_f32 v6, v0, v1
	v_lshl_add_u64 v[0:1], v[98:99], 0, v[32:33]
	s_and_b64 vcc, exec, s[0:1]
	s_mov_b32 s24, s2
	s_mov_b32 s95, s4
	s_mov_b64 s[14:15], s[10:11]
	s_mov_b64 s[12:13], s[8:9]
	global_store_dwordx4 v[34:35], v[36:39], off
	v_cvt_pk_bf16_f32 v31, v26, v27
	global_store_dwordx4 v[24:25], v[28:31], off
	v_cvt_pk_bf16_f32 v23, v18, v19
	global_store_dwordx4 v[16:17], v[20:23], off
	v_cvt_pk_bf16_f32 v15, v10, v11
	global_store_dwordx4 v[8:9], v[12:15], off
	v_cvt_pk_bf16_f32 v7, v2, v3
	global_store_dwordx4 v[0:1], v[4:7], off
	s_cbranch_vccz .LBB0_61
	s_setprio 0
	s_waitcnt vmcnt(0)
	v_readlane_b32 s0, v226, 16
	v_readlane_b32 s36, v226, 30
	v_readlane_b32 s18, v226, 22
	v_readlane_b32 s92, v226, 20
	s_cmpk_gt_u32 s0, 0xff
	v_readlane_b32 s37, v226, 31
	v_readlane_b32 s31, v226, 34
	v_readlane_b32 s42, v226, 29
	v_readlane_b32 s43, v226, 28
	v_readlane_b32 s66, v226, 27
	v_readlane_b32 s67, v226, 26
	v_readlane_b32 s19, v226, 23
	v_readlane_b32 s93, v226, 21
	s_cbranch_scc1 .LBB0_68
	s_barrier

; #define WAIT_V(n) asm volatile("s_waitcnt vmcnt(" #n ")" ::: "memory")
; #define BAR __builtin_amdgcn_s_barrier()
; template <int N, int K, int EPI>
; __device__ void gemm_phase(const u16* __restrict__ A, const u16* __restrict__ Bt, const EpiArgs ea, char* smem, int tid) {
;     ...
;   int tidl = tid;
;   asm volatile("" : "+v"(tidl));
;   const int wid = __builtin_amdgcn_readfirstlane(tidl >> 6);
;   const int lane = tidl & 63, wr = wid >> 2, wc = wid & 3, fr = lane & 15, fq = lane >> 4;
;   const int tb = tidl * 16;
;   unsigned off0b;
;   { int R, C; stage_rc((tidl & 63) * 16 + wid * 1024, R, C); off0b = (unsigned)(R * K + C) * 2u; }
;   const unsigned lds0 = (unsigned)(size_t)(__attribute__((address_space(3))) char*)smem;
;   int pm, pn; tile_map(v, nN, pm, pn);
;   const u16* Ab = A + (size_t)pm * BM * K;
;   const u16* Bb = Bt + (size_t)pn * BM * K;
;   f32x4 acc[2][2][4][2] = {};
;   bf16x8 At[4][2], B0[2][2], B1[2][2];
;   STAGE(SB(0, 0), GP(Bb, 0, 0)); STAGE(SA(0, 0), GP(Ab, 0, 0));
;   STAGE(SB(0, 1), GP(Bb, 1, 0)); STAGE(SA(0, 1), GP(Ab, 1, 0));
;   if (wr == 1) BAR;
;   WAIT_V(4); BAR;
;   STAGE(SB(1, 0), GP(Bb, 0, 1)); STAGE(SA(1, 0), GP(Ab, 0, 1)); STAGE(SB(1, 1), GP(Bb, 1, 1));
;   WAIT_V(6); BAR;
.LBB0_105:
	s_and_b32 s18, s2, 3
	s_add_u32 s2, s12, 0x80
	s_addc_u32 s3, s13, 0
	s_add_u32 s6, s12, 0x20080
	s_addc_u32 s7, s13, 0
	s_add_u32 s8, s4, 0x80
	s_addc_u32 s9, s5, 0
	s_add_u32 s10, s4, 0x20080
	s_addc_u32 s11, s5, 0
	s_add_u32 s14, s12, 0x40080
	s_addc_u32 s15, s13, 0
	s_add_u32 s16, s12, 0x60080
	v_readlane_b32 s19, v227, 60
	v_and_b32_e32 v166, 15, v0
	s_addc_u32 s17, s13, 0
	s_waitcnt vmcnt(2)
	s_barrier
	s_add_i32 s31, s1, s19
	s_mov_b32 m0, s31
	s_nop 0
	global_load_lds_dwordx4 v165, s[2:3]
	v_lshlrev_b32_e32 v3, 2, v0
	v_lshrrev_b32_e32 v167, 4, v1
	s_add_i32 s34, s23, 0x1a000
	s_mov_b32 m0, s34
	s_nop 0
	global_load_lds_dwordx4 v165, s[6:7]
	v_and_b32_e32 v1, 48, v0
	v_lshlrev_b32_e32 v2, 6, v166
	v_and_b32_e32 v3, 32, v3
	s_add_i32 s35, s23, 0x8000
	s_mov_b32 m0, s35
	s_nop 0
	global_load_lds_dwordx4 v165, s[8:9]
	v_bitop3_b32 v2, v2, v3, v1 bitop3:0x36
	s_add_i32 s2, 0, 0x10000
	s_add_i32 s36, s23, 0xa000
	s_mov_b32 m0, s36
	s_nop 0
	global_load_lds_dwordx4 v165, s[10:11]
	v_readlane_b32 s3, v227, 61
	v_add_u32_e32 v4, s2, v2
	s_add_i32 s2, 0, 0x14000
	s_lshl_b32 s22, s18, 5
	s_add_i32 s37, s1, s3
	s_mov_b32 m0, s37
	s_nop 0
	global_load_lds_dwordx4 v165, s[14:15]
	v_add_u32_e32 v5, s2, v2
	s_or_b32 s2, s22, 0xfffffc00
	s_add_i32 s42, s23, 0x1e000
	s_mov_b32 m0, s42
	s_nop 0
	global_load_lds_dwordx4 v165, s[16:17]
	v_writelane_b32 v226, s2, 38
	v_lshlrev_b32_e32 v0, 6, v0
	s_movk_i32 s2, 0x3c0
	s_waitcnt vmcnt(6)
	s_lshl_b32 s1, s18, 12
	s_lshl_b32 s43, s0, 6
	v_add_u32_e32 v6, s19, v2
	v_add_u32_e32 v7, s3, v2
	s_lshl_b32 s0, s0, 13
	v_add_u32_e32 v2, 0, v2
	v_and_or_b32 v0, v0, s2, v1
	v_xad_u32 v168, v0, v3, 0
	s_or_b32 s94, s0, 0x800
	s_or_b32 s2, s0, 0x1000
	s_or_b32 s3, s0, 0x1800
	v_add_u32_e32 v169, s1, v4
	v_add_u32_e32 v170, s0, v2
	v_add_u32_e32 v173, s1, v5
	v_add_u32_e32 v174, s1, v6
	v_add_u32_e32 v175, s1, v7
	v_readlane_b32 s0, v227, 22
	s_add_i32 s66, s23, 0xc000
	s_add_i32 s67, s23, 0xe000
	v_add_u32_e32 v171, s2, v168
	v_add_u32_e32 v172, s3, v168
	s_mov_b32 s97, s0
	v_readlane_b32 s96, v227, 21
	s_barrier
	v_readlane_b32 s1, v227, 23
	v_and_b32_e32 v120, 15, v164
	v_bfe_u32 v121, v164, 4, 2
	v_lshrrev_b32_e32 v122, 3, v120
	v_and_b32_e32 v123, 7, v120
	v_lshlrev_b32_e32 v124, 10, v122
	v_lshl_add_u32 v124, v123, 7, v124
	v_lshl_add_u32 v124, v122, 6, v124
	v_bfe_u32 v125, v120, 1, 2
	v_xor_b32_e32 v125, v125, v121
	v_lshl_add_u32 v124, v125, 4, v124
	v_lshrrev_b32_e32 v126, 8, v164
	v_lshl_add_u32 v170, v126, 13, v124
	v_xor_b32_e32 v171, 64, v170
	v_bfe_u32 v126, v164, 6, 2
	v_lshl_add_u32 v126, v126, 12, v124
	v_add_u32_e32 v169, 0x10000, v126
	v_xor_b32_e32 v173, 64, v169
	v_readfirstlane_b32 s100, v164
	s_lshr_b32 s100, s100, 8
	s_cmp_eq_u32 s100, 1
	s_cbranch_scc0 .Lsp_qkc
	s_setprio 1
.Lsp_qkc:
	s_branch .LBB0_107

.LBB0_110:
	ds_read_b128 v[128:131], v169
	ds_read_b128 v[134:137], v173
	ds_read_b128 v[138:141], v169 offset:2048
	ds_read_b128 v[142:145], v173 offset:2048
	s_add_u32 s16, s14, 0x40080
	s_addc_u32 s17, s15, 0
	s_add_u32 s18, s14, 0x60080
	s_addc_u32 s19, s15, 0
	s_cmp_eq_u32 s3, 12
	s_cselect_b32 s82, s11, s13
	s_cselect_b32 s83, s10, s12
	s_cselect_b32 s88, s9, s5
	s_cselect_b32 s89, s8, s4
	s_nop 0
	ds_read_b128 v[176:179], v170
	ds_read_b128 v[180:183], v171
	ds_read_b128 v[184:187], v170 offset:2048
	ds_read_b128 v[188:191], v171 offset:2048
	ds_read_b128 v[192:195], v170 offset:4096
	ds_read_b128 v[196:199], v171 offset:4096
	ds_read_b128 v[200:203], v170 offset:6144
	ds_read_b128 v[204:207], v171 offset:6144
	s_mov_b32 m0, s66
	s_nop 0
	global_load_lds_dwordx4 v165, s[16:17]
	s_nop 0
	s_mov_b32 m0, s67
	s_nop 0
	global_load_lds_dwordx4 v165, s[18:19]
	ds_read_b128 v[208:211], v169 offset:16384
	ds_read_b128 v[212:215], v173 offset:16384
	ds_read_b128 v[216:219], v169 offset:18432
	ds_read_b128 v[220:223], v173 offset:18432
	s_waitcnt vmcnt(8) lgkmcnt(0)
	s_barrier
	s_waitcnt lgkmcnt(7)
	v_mfma_f32_16x16x32_bf16 v[124:127], v[128:131], v[176:179], v[124:127]
	v_mfma_f32_16x16x32_bf16 v[120:123], v[138:141], v[176:179], v[120:123]
	s_waitcnt lgkmcnt(5)
	v_mfma_f32_16x16x32_bf16 v[116:119], v[128:131], v[184:187], v[116:119]
	v_mfma_f32_16x16x32_bf16 v[112:115], v[138:141], v[184:187], v[112:115]
	s_waitcnt lgkmcnt(3)
	v_mfma_f32_16x16x32_bf16 v[108:111], v[128:131], v[192:195], v[108:111]
	v_mfma_f32_16x16x32_bf16 v[104:107], v[138:141], v[192:195], v[104:107]
	s_waitcnt lgkmcnt(1)
	v_mfma_f32_16x16x32_bf16 v[100:103], v[128:131], v[200:203], v[100:103]
	v_mfma_f32_16x16x32_bf16 v[96:99], v[138:141], v[200:203], v[96:99]
	v_mfma_f32_16x16x32_bf16 v[124:127], v[134:137], v[180:183], v[124:127]
	v_mfma_f32_16x16x32_bf16 v[120:123], v[142:145], v[180:183], v[120:123]
	v_mfma_f32_16x16x32_bf16 v[116:119], v[134:137], v[188:191], v[116:119]
	v_mfma_f32_16x16x32_bf16 v[112:115], v[142:145], v[188:191], v[112:115]
	v_mfma_f32_16x16x32_bf16 v[108:111], v[134:137], v[196:199], v[108:111]
	v_mfma_f32_16x16x32_bf16 v[104:107], v[142:145], v[196:199], v[104:107]
	s_waitcnt lgkmcnt(0)
	v_mfma_f32_16x16x32_bf16 v[100:103], v[134:137], v[204:207], v[100:103]
	v_mfma_f32_16x16x32_bf16 v[96:99], v[142:145], v[204:207], v[96:99]
	s_waitcnt lgkmcnt(3)
	v_mfma_f32_16x16x32_bf16 v[92:95], v[208:211], v[176:179], v[92:95]
	s_waitcnt lgkmcnt(1)
	v_mfma_f32_16x16x32_bf16 v[88:91], v[216:219], v[176:179], v[88:91]
	v_mfma_f32_16x16x32_bf16 v[84:87], v[208:211], v[184:187], v[84:87]
	v_mfma_f32_16x16x32_bf16 v[80:83], v[216:219], v[184:187], v[80:83]
	v_mfma_f32_16x16x32_bf16 v[76:79], v[208:211], v[192:195], v[76:79]
	v_mfma_f32_16x16x32_bf16 v[72:75], v[216:219], v[192:195], v[72:75]
	v_mfma_f32_16x16x32_bf16 v[68:71], v[208:211], v[200:203], v[68:71]
	v_mfma_f32_16x16x32_bf16 v[64:67], v[216:219], v[200:203], v[64:67]
	v_mfma_f32_16x16x32_bf16 v[92:95], v[212:215], v[180:183], v[92:95]
	s_waitcnt lgkmcnt(0)
	v_mfma_f32_16x16x32_bf16 v[88:91], v[220:223], v[180:183], v[88:91]
	v_mfma_f32_16x16x32_bf16 v[84:87], v[212:215], v[188:191], v[84:87]
	v_mfma_f32_16x16x32_bf16 v[80:83], v[220:223], v[188:191], v[80:83]
	v_mfma_f32_16x16x32_bf16 v[76:79], v[212:215], v[196:199], v[76:79]
	v_mfma_f32_16x16x32_bf16 v[72:75], v[220:223], v[196:199], v[72:75]
	v_mfma_f32_16x16x32_bf16 v[68:71], v[212:215], v[204:207], v[68:71]
	v_mfma_f32_16x16x32_bf16 v[64:67], v[220:223], v[204:207], v[64:67]
	s_barrier
	s_cselect_b32 s70, 0, s7
	s_lshl_b64 s[92:93], s[70:71], 1
	s_add_u32 s16, s83, s92
	s_addc_u32 s17, s82, s93
	s_add_u32 s18, s16, 0x20000
	s_mov_b32 m0, s24
	s_nop 0
	global_load_lds_dwordx4 v165, s[16:17]
	s_addc_u32 s19, s17, 0
	s_mov_b32 m0, s25
	s_nop 0
	global_load_lds_dwordx4 v165, s[18:19]
	ds_read_b128 v[176:179], v170 offset:16384
	ds_read_b128 v[180:183], v171 offset:16384
	ds_read_b128 v[184:187], v170 offset:18432
	ds_read_b128 v[188:191], v171 offset:18432
	ds_read_b128 v[192:195], v170 offset:20480
	ds_read_b128 v[196:199], v171 offset:20480
	ds_read_b128 v[200:203], v170 offset:22528
	ds_read_b128 v[204:207], v171 offset:22528
	s_add_u32 s18, s89, s92
	s_addc_u32 s19, s88, s93
	s_add_u32 s88, s18, 0x20000
	s_mov_b32 m0, s23
	s_nop 0
	global_load_lds_dwordx4 v165, s[18:19]
	s_addc_u32 s89, s19, 0
	s_mov_b32 m0, s26
	s_nop 0
	global_load_lds_dwordx4 v165, s[88:89]
	s_add_u32 s83, s83, 0x40000
	s_addc_u32 s82, s82, 0
	s_add_u32 s88, s83, s92
	s_addc_u32 s89, s82, s93
	s_add_u32 s92, s88, 0x20000
	s_mov_b32 m0, s27
	s_nop 0
	global_load_lds_dwordx4 v165, s[88:89]
	s_addc_u32 s93, s89, 0
	s_mov_b32 m0, s28
	s_nop 0
	global_load_lds_dwordx4 v165, s[92:93]
	s_waitcnt vmcnt(8) lgkmcnt(0)
	s_barrier
	s_waitcnt lgkmcnt(7)
	v_mfma_f32_16x16x32_bf16 v[60:63], v[128:131], v[176:179], v[60:63]
	v_mfma_f32_16x16x32_bf16 v[56:59], v[138:141], v[176:179], v[56:59]
	s_waitcnt lgkmcnt(5)
	v_mfma_f32_16x16x32_bf16 v[52:55], v[128:131], v[184:187], v[52:55]
	v_mfma_f32_16x16x32_bf16 v[48:51], v[138:141], v[184:187], v[48:51]
	s_waitcnt lgkmcnt(3)
	v_mfma_f32_16x16x32_bf16 v[44:47], v[128:131], v[192:195], v[44:47]
	v_mfma_f32_16x16x32_bf16 v[40:43], v[138:141], v[192:195], v[40:43]
	s_waitcnt lgkmcnt(1)
	v_mfma_f32_16x16x32_bf16 v[36:39], v[128:131], v[200:203], v[36:39]
	v_mfma_f32_16x16x32_bf16 v[32:35], v[138:141], v[200:203], v[32:35]
	v_mfma_f32_16x16x32_bf16 v[60:63], v[134:137], v[180:183], v[60:63]
	v_mfma_f32_16x16x32_bf16 v[56:59], v[142:145], v[180:183], v[56:59]
	v_mfma_f32_16x16x32_bf16 v[52:55], v[134:137], v[188:191], v[52:55]
	v_mfma_f32_16x16x32_bf16 v[48:51], v[142:145], v[188:191], v[48:51]
	v_mfma_f32_16x16x32_bf16 v[44:47], v[134:137], v[196:199], v[44:47]
	v_mfma_f32_16x16x32_bf16 v[40:43], v[142:145], v[196:199], v[40:43]
	s_waitcnt lgkmcnt(0)
	v_mfma_f32_16x16x32_bf16 v[36:39], v[134:137], v[204:207], v[36:39]
	v_mfma_f32_16x16x32_bf16 v[32:35], v[142:145], v[204:207], v[32:35]
	v_mfma_f32_16x16x32_bf16 v[28:31], v[208:211], v[176:179], v[28:31]
	v_mfma_f32_16x16x32_bf16 v[24:27], v[216:219], v[176:179], v[24:27]
	v_mfma_f32_16x16x32_bf16 v[20:23], v[208:211], v[184:187], v[20:23]
	v_mfma_f32_16x16x32_bf16 v[16:19], v[216:219], v[184:187], v[16:19]
	v_mfma_f32_16x16x32_bf16 v[12:15], v[208:211], v[192:195], v[12:15]
	v_mfma_f32_16x16x32_bf16 v[8:11], v[216:219], v[192:195], v[8:11]
	v_mfma_f32_16x16x32_bf16 v[4:7], v[208:211], v[200:203], v[4:7]
	v_mfma_f32_16x16x32_bf16 v[0:3], v[216:219], v[200:203], v[0:3]
	v_mfma_f32_16x16x32_bf16 v[28:31], v[212:215], v[180:183], v[28:31]
	v_mfma_f32_16x16x32_bf16 v[24:27], v[220:223], v[180:183], v[24:27]
	v_mfma_f32_16x16x32_bf16 v[20:23], v[212:215], v[188:191], v[20:23]
	v_mfma_f32_16x16x32_bf16 v[16:19], v[220:223], v[188:191], v[16:19]
	v_mfma_f32_16x16x32_bf16 v[12:15], v[212:215], v[196:199], v[12:15]
	v_mfma_f32_16x16x32_bf16 v[8:11], v[220:223], v[196:199], v[8:11]
	v_mfma_f32_16x16x32_bf16 v[4:7], v[212:215], v[204:207], v[4:7]
	v_mfma_f32_16x16x32_bf16 v[0:3], v[220:223], v[204:207], v[0:3]
	s_barrier
	ds_read_b128 v[128:131], v169 offset:32768
	ds_read_b128 v[134:137], v173 offset:32768
	ds_read_b128 v[138:141], v169 offset:34816
	ds_read_b128 v[142:145], v173 offset:34816
	ds_read_b128 v[176:179], v170 offset:32768
	ds_read_b128 v[180:183], v171 offset:32768
	ds_read_b128 v[184:187], v170 offset:34816
	ds_read_b128 v[188:191], v171 offset:34816
	ds_read_b128 v[192:195], v170 offset:36864
	ds_read_b128 v[196:199], v171 offset:36864
	ds_read_b128 v[200:203], v170 offset:38912
	ds_read_b128 v[204:207], v171 offset:38912
	s_add_u32 s88, s18, 0x40000
	s_addc_u32 s89, s19, 0
	s_add_u32 s92, s18, 0x60000
	s_mov_b32 m0, s29
	s_nop 0
	global_load_lds_dwordx4 v165, s[88:89]
	s_addc_u32 s93, s19, 0
	s_mov_b32 m0, s30
	s_nop 0
	global_load_lds_dwordx4 v165, s[92:93]
	ds_read_b128 v[208:211], v169 offset:49152
	ds_read_b128 v[212:215], v173 offset:49152
	ds_read_b128 v[216:219], v169 offset:51200
	ds_read_b128 v[220:223], v173 offset:51200
	s_waitcnt vmcnt(8) lgkmcnt(0)
	s_barrier
	s_waitcnt lgkmcnt(7)
	v_mfma_f32_16x16x32_bf16 v[124:127], v[128:131], v[176:179], v[124:127]
	v_mfma_f32_16x16x32_bf16 v[120:123], v[138:141], v[176:179], v[120:123]
	s_waitcnt lgkmcnt(5)
	v_mfma_f32_16x16x32_bf16 v[116:119], v[128:131], v[184:187], v[116:119]
	v_mfma_f32_16x16x32_bf16 v[112:115], v[138:141], v[184:187], v[112:115]
	s_waitcnt lgkmcnt(3)
	v_mfma_f32_16x16x32_bf16 v[108:111], v[128:131], v[192:195], v[108:111]
	v_mfma_f32_16x16x32_bf16 v[104:107], v[138:141], v[192:195], v[104:107]
	s_waitcnt lgkmcnt(1)
	v_mfma_f32_16x16x32_bf16 v[100:103], v[128:131], v[200:203], v[100:103]
	v_mfma_f32_16x16x32_bf16 v[96:99], v[138:141], v[200:203], v[96:99]
	v_mfma_f32_16x16x32_bf16 v[124:127], v[134:137], v[180:183], v[124:127]
	v_mfma_f32_16x16x32_bf16 v[120:123], v[142:145], v[180:183], v[120:123]
	v_mfma_f32_16x16x32_bf16 v[116:119], v[134:137], v[188:191], v[116:119]
	v_mfma_f32_16x16x32_bf16 v[112:115], v[142:145], v[188:191], v[112:115]
	v_mfma_f32_16x16x32_bf16 v[108:111], v[134:137], v[196:199], v[108:111]
	v_mfma_f32_16x16x32_bf16 v[104:107], v[142:145], v[196:199], v[104:107]
	s_waitcnt lgkmcnt(0)
	v_mfma_f32_16x16x32_bf16 v[100:103], v[134:137], v[204:207], v[100:103]
	v_mfma_f32_16x16x32_bf16 v[96:99], v[142:145], v[204:207], v[96:99]
	s_waitcnt lgkmcnt(3)
	v_mfma_f32_16x16x32_bf16 v[92:95], v[208:211], v[176:179], v[92:95]
	s_waitcnt lgkmcnt(1)
	v_mfma_f32_16x16x32_bf16 v[88:91], v[216:219], v[176:179], v[88:91]
	v_mfma_f32_16x16x32_bf16 v[84:87], v[208:211], v[184:187], v[84:87]
	v_mfma_f32_16x16x32_bf16 v[80:83], v[216:219], v[184:187], v[80:83]
	v_mfma_f32_16x16x32_bf16 v[76:79], v[208:211], v[192:195], v[76:79]
	v_mfma_f32_16x16x32_bf16 v[72:75], v[216:219], v[192:195], v[72:75]
	v_mfma_f32_16x16x32_bf16 v[68:71], v[208:211], v[200:203], v[68:71]
	v_mfma_f32_16x16x32_bf16 v[64:67], v[216:219], v[200:203], v[64:67]
	v_mfma_f32_16x16x32_bf16 v[92:95], v[212:215], v[180:183], v[92:95]
	s_waitcnt lgkmcnt(0)
	v_mfma_f32_16x16x32_bf16 v[88:91], v[220:223], v[180:183], v[88:91]
	v_mfma_f32_16x16x32_bf16 v[84:87], v[212:215], v[188:191], v[84:87]
	v_mfma_f32_16x16x32_bf16 v[80:83], v[220:223], v[188:191], v[80:83]
	v_mfma_f32_16x16x32_bf16 v[76:79], v[212:215], v[196:199], v[76:79]
	v_mfma_f32_16x16x32_bf16 v[72:75], v[220:223], v[196:199], v[72:75]
	v_mfma_f32_16x16x32_bf16 v[68:71], v[212:215], v[204:207], v[68:71]
	v_mfma_f32_16x16x32_bf16 v[64:67], v[220:223], v[204:207], v[64:67]
	s_barrier
; template <int N, int K, int EPI>
; __device__ void gemm_phase(const u16* __restrict__ A, const u16* __restrict__ Bt, const EpiArgs ea, char* smem, int tid) {
;     ...
;         if (pn == 4 || pn == 5) {
;           u16* vt = ea.o2;
; #pragma unroll
;           for (int ai = 0; ai < 2; ++ai)
; #pragma unroll
;             for (int bj = 0; bj < 2; ++bj)
; #pragma unroll
;               for (int m = 0; m < 4; ++m)
; #pragma unroll
;                 for (int n = 0; n < 2; ++n) {
;                   f32x4 vv = acc[ai][bj][m][n];
;                   const bool b0 = fr_e & 1, b1 = fr_e & 2;
;                   { float sA = b0 ? vv[0] : vv[1], sB = b0 ? vv[2] : vv[3];
;                     float rA = __shfl_xor(sA, 1), rB = __shfl_xor(sB, 1);
;                     if (b0) { vv[0] = rA; vv[2] = rB; } else { vv[1] = rA; vv[3] = rB; } }
;                   { float sC = b1 ? vv[0] : vv[2], sD = b1 ? vv[1] : vv[3];
;                     float rC = __shfl_xor(sC, 2), rD = __shfl_xor(sD, 2);
;                     if (b1) { vv[0] = rC; vv[1] = rD; } else { vv[2] = rC; vv[3] = rD; } }
;                   int row = brow + ai * HALF + wr * 64 + m * 16 + (fr_e & ~3);
;                   int col = (pn - 4) * 256 + bj * HALF + wc * 32 + fq_e * 8 + n * 4 + (fr_e & 3);
;                   int b = row >> 12, sq = row & 4095, hh = col >> 6, dh = col & 63;
;                   u32x2 o = {pk_bf16(vv[0], vv[1]), pk_bf16(vv[2], vv[3])};
;                   *(u32x2*)(vt + ((size_t)(b * 8 + hh) * 64 + dh) * SEQ + sq) = o;
;                 }
;         } else {
;           u16* base; float sc = 1.f; int cbase; bool headed;
;           if (pn < 2) { base = ea.o0; sc = QSCALE; cbase = pn * 256; headed = true; }
;           else if (pn < 4) { base = ea.o1; cbase = (pn - 2) * 256; headed = true; }
;           else { base = ea.o3; cbase = (pn - 6) * 256; headed = false; }
	s_or_b32 s70, s70, 64
	s_add_u32 s88, s16, 0x80
	s_addc_u32 s89, s17, 0
	s_add_u32 s16, s16, 0x20080
	s_mov_b32 m0, s31
	s_nop 0
	global_load_lds_dwordx4 v165, s[88:89]
	s_addc_u32 s17, s17, 0
	s_mov_b32 m0, s34
	s_nop 0
	global_load_lds_dwordx4 v165, s[16:17]
	ds_read_b128 v[176:179], v170 offset:49152
	ds_read_b128 v[180:183], v171 offset:49152
	ds_read_b128 v[184:187], v170 offset:51200
	ds_read_b128 v[188:191], v171 offset:51200
	ds_read_b128 v[192:195], v170 offset:53248
	ds_read_b128 v[196:199], v171 offset:53248
	ds_read_b128 v[200:203], v170 offset:55296
	ds_read_b128 v[204:207], v171 offset:55296
	s_add_u32 s16, s18, 0x80
	s_addc_u32 s17, s19, 0
	s_add_u32 s18, s18, 0x20080
	s_mov_b32 m0, s35
	s_nop 0
	global_load_lds_dwordx4 v165, s[16:17]
	s_addc_u32 s19, s19, 0
	s_mov_b32 m0, s36
	s_nop 0
	global_load_lds_dwordx4 v165, s[18:19]
	s_lshl_b64 s[16:17], s[70:71], 1
	s_add_u32 s16, s83, s16
	s_addc_u32 s17, s82, s17
	s_add_u32 s18, s16, 0x20000
	s_mov_b32 m0, s37
	s_nop 0
	global_load_lds_dwordx4 v165, s[16:17]
	s_addc_u32 s19, s17, 0
	s_mov_b32 m0, s42
	s_nop 0
	global_load_lds_dwordx4 v165, s[18:19]
	s_waitcnt vmcnt(8) lgkmcnt(0)
	s_barrier
	s_waitcnt lgkmcnt(7)
	v_mfma_f32_16x16x32_bf16 v[60:63], v[128:131], v[176:179], v[60:63]
	v_mfma_f32_16x16x32_bf16 v[56:59], v[138:141], v[176:179], v[56:59]
	s_waitcnt lgkmcnt(5)
	v_mfma_f32_16x16x32_bf16 v[52:55], v[128:131], v[184:187], v[52:55]
	v_mfma_f32_16x16x32_bf16 v[48:51], v[138:141], v[184:187], v[48:51]
	s_waitcnt lgkmcnt(3)
	v_mfma_f32_16x16x32_bf16 v[44:47], v[128:131], v[192:195], v[44:47]
	v_mfma_f32_16x16x32_bf16 v[40:43], v[138:141], v[192:195], v[40:43]
	s_waitcnt lgkmcnt(1)
	v_mfma_f32_16x16x32_bf16 v[36:39], v[128:131], v[200:203], v[36:39]
	v_mfma_f32_16x16x32_bf16 v[32:35], v[138:141], v[200:203], v[32:35]
	v_mfma_f32_16x16x32_bf16 v[60:63], v[134:137], v[180:183], v[60:63]
	v_mfma_f32_16x16x32_bf16 v[56:59], v[142:145], v[180:183], v[56:59]
	v_mfma_f32_16x16x32_bf16 v[52:55], v[134:137], v[188:191], v[52:55]
	v_mfma_f32_16x16x32_bf16 v[48:51], v[142:145], v[188:191], v[48:51]
	v_mfma_f32_16x16x32_bf16 v[44:47], v[134:137], v[196:199], v[44:47]
	v_mfma_f32_16x16x32_bf16 v[40:43], v[142:145], v[196:199], v[40:43]
	s_waitcnt lgkmcnt(0)
	v_mfma_f32_16x16x32_bf16 v[36:39], v[134:137], v[204:207], v[36:39]
	v_mfma_f32_16x16x32_bf16 v[32:35], v[142:145], v[204:207], v[32:35]
	v_mfma_f32_16x16x32_bf16 v[28:31], v[208:211], v[176:179], v[28:31]
	v_mfma_f32_16x16x32_bf16 v[24:27], v[216:219], v[176:179], v[24:27]
	v_mfma_f32_16x16x32_bf16 v[20:23], v[208:211], v[184:187], v[20:23]
	v_mfma_f32_16x16x32_bf16 v[16:19], v[216:219], v[184:187], v[16:19]
	v_mfma_f32_16x16x32_bf16 v[12:15], v[208:211], v[192:195], v[12:15]
	v_mfma_f32_16x16x32_bf16 v[8:11], v[216:219], v[192:195], v[8:11]
	v_mfma_f32_16x16x32_bf16 v[4:7], v[208:211], v[200:203], v[4:7]
	v_mfma_f32_16x16x32_bf16 v[0:3], v[216:219], v[200:203], v[0:3]
	v_mfma_f32_16x16x32_bf16 v[28:31], v[212:215], v[180:183], v[28:31]
	v_mfma_f32_16x16x32_bf16 v[24:27], v[220:223], v[180:183], v[24:27]
	v_mfma_f32_16x16x32_bf16 v[20:23], v[212:215], v[188:191], v[20:23]
	v_mfma_f32_16x16x32_bf16 v[16:19], v[220:223], v[188:191], v[16:19]
	v_mfma_f32_16x16x32_bf16 v[12:15], v[212:215], v[196:199], v[12:15]
	v_mfma_f32_16x16x32_bf16 v[8:11], v[220:223], v[196:199], v[8:11]
	v_mfma_f32_16x16x32_bf16 v[4:7], v[212:215], v[204:207], v[4:7]
	v_mfma_f32_16x16x32_bf16 v[0:3], v[220:223], v[204:207], v[0:3]
	s_add_i32 s3, s3, 2
	s_addk_i32 s7, 0x80
	s_add_u32 s14, s14, 0x100
	s_addc_u32 s15, s15, 0
	s_cmp_gt_u32 s3, 13
	s_barrier
	s_cbranch_scc0 .LBB0_110
	s_lshl_b32 s3, s97, 8
	s_and_b32 s4, s96, -2
	v_mov_b32_e32 v176, v167
	v_mov_b32_e32 v132, v166
	s_cmp_lg_u32 s4, 4
	s_mov_b64 s[4:5], -1
	s_mov_b32 s19, 0x3ffc0
	s_cbranch_scc0 .LBB0_184
	s_cmp_gt_i32 s96, 1
	s_mov_b64 s[14:15], -1
	s_cbranch_scc0 .LBB0_117
	s_lshl_b32 s7, s96, 8
	s_cmp_gt_u32 s96, 3
	s_mov_b64 s[4:5], -1
	s_cbranch_scc0 .LBB0_115
	s_add_i32 s18, s7, 0xfffffa00
	s_mov_b64 s[4:5], 0

; #define WAIT_V(n) asm volatile("s_waitcnt vmcnt(" #n ")" ::: "memory")
; #define BAR __builtin_amdgcn_s_barrier()
; template <int N, int K, int EPI>
; __device__ void gemm_phase(const u16* __restrict__ A, const u16* __restrict__ Bt, const EpiArgs ea, char* smem, int tid) {
;     ...
;   WAIT_V(0);
;   if (wr == 0) BAR;
;   __syncthreads();
.LBB0_186:
	s_setprio 0
	s_waitcnt vmcnt(0)
	v_readlane_b32 s0, v226, 37
	v_readlane_b32 s34, v226, 32
	v_readlane_b32 s36, v226, 30
	v_readlane_b32 s18, v226, 22
	v_readlane_b32 s92, v226, 20
	s_cmpk_gt_u32 s0, 0xff
	v_readlane_b32 s22, v226, 11
	v_readlane_b32 s35, v226, 33
	v_readlane_b32 s37, v226, 31
	v_readlane_b32 s31, v226, 34
	v_readlane_b32 s42, v226, 29
	v_readlane_b32 s43, v226, 28
	v_readlane_b32 s82, v226, 25
	v_readlane_b32 s83, v226, 24
	v_readlane_b32 s19, v226, 23
	v_readlane_b32 s93, v226, 21
	s_cbranch_scc1 .LBB0_188
	s_barrier

; #define WAIT_V(n) asm volatile("s_waitcnt vmcnt(" #n ")" ::: "memory")
; #define BAR __builtin_amdgcn_s_barrier()
; template <int N, int K, int EPI>
; __device__ void gemm_phase(const u16* __restrict__ A, const u16* __restrict__ Bt, const EpiArgs ea, char* smem, int tid) {
;     ...
;   int tidl = tid;
;   asm volatile("" : "+v"(tidl));
;   const int wid = __builtin_amdgcn_readfirstlane(tidl >> 6);
;   const int lane = tidl & 63, wr = wid >> 2, wc = wid & 3, fr = lane & 15, fq = lane >> 4;
;   const int tb = tidl * 16;
;   unsigned off0b;
;   { int R, C; stage_rc((tidl & 63) * 16 + wid * 1024, R, C); off0b = (unsigned)(R * K + C) * 2u; }
;   const unsigned lds0 = (unsigned)(size_t)(__attribute__((address_space(3))) char*)smem;
;   int pm, pn; tile_map(v, nN, pm, pn);
;   const u16* Ab = A + (size_t)pm * BM * K;
;   const u16* Bb = Bt + (size_t)pn * BM * K;
;   f32x4 acc[2][2][4][2] = {};
;   bf16x8 At[4][2], B0[2][2], B1[2][2];
;   STAGE(SB(0, 0), GP(Bb, 0, 0)); STAGE(SA(0, 0), GP(Ab, 0, 0));
;   STAGE(SB(0, 1), GP(Bb, 1, 0)); STAGE(SA(0, 1), GP(Ab, 1, 0));
;   if (wr == 1) BAR;
;   WAIT_V(4); BAR;
;   STAGE(SB(1, 0), GP(Bb, 0, 1)); STAGE(SA(1, 0), GP(Ab, 0, 1)); STAGE(SB(1, 1), GP(Bb, 1, 1));
;   WAIT_V(6); BAR;
;   while (true) {
;     const int vn = v + gridDim.x;
;     const bool has_next = vn < nwg;
;     int pmn = pm, pnn = pn;
;     if (has_next) tile_map(vn, nN, pmn, pnn);
.LBB0_216:
	s_and_b32 s42, s2, 3
	s_add_u32 s2, s8, 0x80
	s_addc_u32 s3, s9, 0
	s_add_u32 s4, s8, 0x58080
	s_addc_u32 s5, s9, 0
	s_add_u32 s10, s6, 0x80
	s_addc_u32 s11, s7, 0
	s_add_u32 s12, s6, 0x58080
	s_addc_u32 s13, s7, 0
	s_add_u32 s14, s8, 0xb0080
	s_addc_u32 s15, s9, 0
	s_add_u32 s36, s8, 0x108080
	v_readlane_b32 s43, v227, 60
	s_addc_u32 s37, s9, 0
	s_waitcnt vmcnt(2)
	s_barrier
	s_add_i32 s27, s1, s43
	s_mov_b32 m0, s27
	s_nop 0
	global_load_lds_dwordx4 v130, s[2:3]
	v_and_b32_e32 v131, 15, v0
	s_add_i32 s28, s19, 0x1a000
	s_mov_b32 m0, s28
	s_nop 0
	global_load_lds_dwordx4 v130, s[4:5]
	v_lshlrev_b32_e32 v3, 2, v0
	v_lshrrev_b32_e32 v132, 4, v1
	s_add_i32 s29, s19, 0x8000
	s_mov_b32 m0, s29
	s_nop 0
	global_load_lds_dwordx4 v130, s[10:11]
	v_and_b32_e32 v1, 48, v0
	v_lshlrev_b32_e32 v2, 6, v131
	v_and_b32_e32 v3, 32, v3
	s_add_i32 s30, s19, 0xa000
	s_mov_b32 m0, s30
	s_nop 0
	global_load_lds_dwordx4 v130, s[12:13]
	v_readlane_b32 s3, v227, 61
	v_bitop3_b32 v2, v2, v3, v1 bitop3:0x36
	s_add_i32 s2, 0, 0x10000
	s_add_i32 s31, s1, s3
	s_mov_b32 m0, s31
	s_nop 0
	global_load_lds_dwordx4 v130, s[14:15]
	v_add_u32_e32 v4, s2, v2
	s_add_i32 s2, 0, 0x14000
	s_add_i32 s34, s19, 0x1e000
	s_mov_b32 m0, s34
	s_nop 0
	global_load_lds_dwordx4 v130, s[36:37]
	v_add_u32_e32 v5, s2, v2
	v_lshlrev_b32_e32 v0, 6, v0
	s_movk_i32 s2, 0x3c0
	s_waitcnt vmcnt(6)
	s_lshl_b32 s1, s42, 12
	s_lshl_b32 s35, s0, 6
	v_add_u32_e32 v6, s43, v2
	v_add_u32_e32 v7, s3, v2
	s_lshl_b32 s0, s0, 13
	v_add_u32_e32 v2, 0, v2
	v_and_or_b32 v0, v0, s2, v1
	v_xad_u32 v134, v0, v3, 0
	s_or_b32 s43, s0, 0x800
	s_or_b32 s2, s0, 0x1000
	s_or_b32 s3, s0, 0x1800
	v_add_u32_e32 v135, s1, v4
	v_add_u32_e32 v136, s0, v2
	v_add_u32_e32 v139, s1, v5
	v_add_u32_e32 v140, s1, v6
	v_add_u32_e32 v141, s1, v7
	v_readlane_b32 s0, v227, 9
	v_readlane_b32 s73, v227, 8
	s_add_i32 s36, s19, 0xc000
	s_add_i32 s37, s19, 0xe000
	s_lshl_b32 s42, s42, 5
	v_add_u32_e32 v137, s2, v134
	v_add_u32_e32 v138, s3, v134
	s_mov_b32 s88, s0
	s_mov_b32 s95, s94
	s_mov_b32 s66, s94
	s_mov_b32 s67, s0
	s_mov_b32 s72, s73
	s_barrier
	v_readlane_b32 s1, v227, 10
	v_and_b32_e32 v120, 15, v164
	v_bfe_u32 v121, v164, 4, 2
	v_lshrrev_b32_e32 v122, 3, v120
	v_and_b32_e32 v123, 7, v120
	v_lshlrev_b32_e32 v124, 10, v122
	v_lshl_add_u32 v124, v123, 7, v124
	v_lshl_add_u32 v124, v122, 6, v124
	v_bfe_u32 v125, v120, 1, 2
	v_xor_b32_e32 v125, v125, v121
	v_lshl_add_u32 v124, v125, 4, v124
	v_lshrrev_b32_e32 v126, 8, v164
	v_lshl_add_u32 v136, v126, 13, v124
	v_xor_b32_e32 v137, 64, v136
	v_bfe_u32 v126, v164, 6, 2
	v_lshl_add_u32 v126, v126, 12, v124
	v_add_u32_e32 v135, 0x10000, v126
	v_xor_b32_e32 v139, 64, v135
	v_readfirstlane_b32 s100, v164
	s_lshr_b32 s100, s100, 8
	s_cmp_eq_u32 s100, 1
	s_cbranch_scc0 .Lsp_down
	s_setprio 1
.Lsp_down:
.LBB0_217:
	s_add_i32 s66, s66, s33
	s_cmpk_gt_i32 s66, 0x1ff
	s_cselect_b64 s[0:1], -1, 0
	s_and_b64 vcc, exec, s[0:1]
	s_cbranch_vccnz .LBB0_219
	s_lshl_b32 s3, s66, 6
	s_ashr_i32 s2, s66, 3
	s_and_b32 s3, s3, 0x1c0
	s_add_i32 s2, s3, s2
	s_ashr_i32 s3, s2, 31
	s_lshr_b32 s3, s3, 27
	s_add_i32 s3, s2, s3
	s_ashr_i32 s4, s3, 5
	s_and_b32 s3, s3, 0xffe0
	s_sub_i32 s2, s2, s3
	s_bfe_i32 s3, s2, 0x80000
	s_bfe_u32 s3, s3, 0x3000c
	s_add_i32 s3, s2, s3
	s_bfe_i32 s5, s3, 0x80000
	s_and_b32 s3, s3, 0xf8
	s_sub_i32 s2, s2, s3
	s_lshl_b32 s4, s4, 3
	s_sext_i32_i16 s5, s5
	s_sext_i32_i8 s2, s2
	s_add_i32 s67, s4, s2
	s_ashr_i32 s72, s5, 3

.LBB0_220:
	ds_read_b128 v[142:145], v135
	ds_read_b128 v[166:169], v139
	ds_read_b128 v[170:173], v135 offset:2048
	ds_read_b128 v[174:177], v139 offset:2048
	s_add_u32 s12, s10, 0xb0080
	s_addc_u32 s13, s11, 0
	s_add_u32 s14, s10, 0x108080
	s_addc_u32 s15, s11, 0
	s_cmp_eq_u32 s89, 40
	s_cselect_b32 s82, s5, s9
	s_cselect_b32 s83, s4, s8
	s_cselect_b32 s92, s3, s7
	s_cselect_b32 s93, s2, s6
	s_nop 0
	ds_read_b128 v[178:181], v136
	ds_read_b128 v[182:185], v137
	ds_read_b128 v[186:189], v136 offset:2048
	ds_read_b128 v[190:193], v137 offset:2048
	ds_read_b128 v[194:197], v136 offset:4096
	ds_read_b128 v[198:201], v137 offset:4096
	ds_read_b128 v[202:205], v136 offset:6144
	ds_read_b128 v[206:209], v137 offset:6144
	s_mov_b32 m0, s36
	s_nop 0
	global_load_lds_dwordx4 v130, s[12:13]
	s_nop 0
	s_mov_b32 m0, s37
	s_nop 0
	global_load_lds_dwordx4 v130, s[14:15]
	ds_read_b128 v[210:213], v135 offset:16384
	ds_read_b128 v[214:217], v139 offset:16384
	ds_read_b128 v[218:221], v135 offset:18432
	ds_read_b128 v[222:225], v139 offset:18432
	s_waitcnt vmcnt(8) lgkmcnt(0)
	s_barrier
	s_waitcnt lgkmcnt(7)
	v_mfma_f32_16x16x32_bf16 v[124:127], v[142:145], v[178:181], v[124:127]
	v_mfma_f32_16x16x32_bf16 v[120:123], v[170:173], v[178:181], v[120:123]
	s_waitcnt lgkmcnt(5)
	v_mfma_f32_16x16x32_bf16 v[116:119], v[142:145], v[186:189], v[116:119]
	v_mfma_f32_16x16x32_bf16 v[112:115], v[170:173], v[186:189], v[112:115]
	s_waitcnt lgkmcnt(3)
	v_mfma_f32_16x16x32_bf16 v[108:111], v[142:145], v[194:197], v[108:111]
	v_mfma_f32_16x16x32_bf16 v[104:107], v[170:173], v[194:197], v[104:107]
	s_waitcnt lgkmcnt(1)
	v_mfma_f32_16x16x32_bf16 v[100:103], v[142:145], v[202:205], v[100:103]
	v_mfma_f32_16x16x32_bf16 v[96:99], v[170:173], v[202:205], v[96:99]
	v_mfma_f32_16x16x32_bf16 v[124:127], v[166:169], v[182:185], v[124:127]
	v_mfma_f32_16x16x32_bf16 v[120:123], v[174:177], v[182:185], v[120:123]
	v_mfma_f32_16x16x32_bf16 v[116:119], v[166:169], v[190:193], v[116:119]
	v_mfma_f32_16x16x32_bf16 v[112:115], v[174:177], v[190:193], v[112:115]
	v_mfma_f32_16x16x32_bf16 v[108:111], v[166:169], v[198:201], v[108:111]
	v_mfma_f32_16x16x32_bf16 v[104:107], v[174:177], v[198:201], v[104:107]
	s_waitcnt lgkmcnt(0)
	v_mfma_f32_16x16x32_bf16 v[100:103], v[166:169], v[206:209], v[100:103]
	v_mfma_f32_16x16x32_bf16 v[96:99], v[174:177], v[206:209], v[96:99]
	s_waitcnt lgkmcnt(3)
	v_mfma_f32_16x16x32_bf16 v[92:95], v[210:213], v[178:181], v[92:95]
	s_waitcnt lgkmcnt(1)
	v_mfma_f32_16x16x32_bf16 v[88:91], v[218:221], v[178:181], v[88:91]
	v_mfma_f32_16x16x32_bf16 v[84:87], v[210:213], v[186:189], v[84:87]
	v_mfma_f32_16x16x32_bf16 v[80:83], v[218:221], v[186:189], v[80:83]
	v_mfma_f32_16x16x32_bf16 v[76:79], v[210:213], v[194:197], v[76:79]
	v_mfma_f32_16x16x32_bf16 v[72:75], v[218:221], v[194:197], v[72:75]
	v_mfma_f32_16x16x32_bf16 v[68:71], v[210:213], v[202:205], v[68:71]
	v_mfma_f32_16x16x32_bf16 v[64:67], v[218:221], v[202:205], v[64:67]
	v_mfma_f32_16x16x32_bf16 v[92:95], v[214:217], v[182:185], v[92:95]
	s_waitcnt lgkmcnt(0)
	v_mfma_f32_16x16x32_bf16 v[88:91], v[222:225], v[182:185], v[88:91]
	v_mfma_f32_16x16x32_bf16 v[84:87], v[214:217], v[190:193], v[84:87]
	v_mfma_f32_16x16x32_bf16 v[80:83], v[222:225], v[190:193], v[80:83]
	v_mfma_f32_16x16x32_bf16 v[76:79], v[214:217], v[198:201], v[76:79]
	v_mfma_f32_16x16x32_bf16 v[72:75], v[222:225], v[198:201], v[72:75]
	v_mfma_f32_16x16x32_bf16 v[68:71], v[214:217], v[206:209], v[68:71]
	v_mfma_f32_16x16x32_bf16 v[64:67], v[222:225], v[206:209], v[64:67]
	s_barrier
	s_cselect_b32 s70, 0, s94
	s_lshl_b64 s[96:97], s[70:71], 1
	s_add_u32 s12, s83, s96
	s_addc_u32 s13, s82, s97
	s_add_u32 s14, s12, 0x58000
	s_mov_b32 m0, s20
	s_nop 0
	global_load_lds_dwordx4 v130, s[12:13]
	s_addc_u32 s15, s13, 0
	s_mov_b32 m0, s21
	s_nop 0
	global_load_lds_dwordx4 v130, s[14:15]
	ds_read_b128 v[178:181], v136 offset:16384
	ds_read_b128 v[182:185], v137 offset:16384
	ds_read_b128 v[186:189], v136 offset:18432
	ds_read_b128 v[190:193], v137 offset:18432
	ds_read_b128 v[194:197], v136 offset:20480
	ds_read_b128 v[198:201], v137 offset:20480
	ds_read_b128 v[202:205], v136 offset:22528
	ds_read_b128 v[206:209], v137 offset:22528
	s_add_u32 s14, s93, s96
	s_addc_u32 s15, s92, s97
	s_add_u32 s92, s14, 0x58000
	s_mov_b32 m0, s19
	s_nop 0
	global_load_lds_dwordx4 v130, s[14:15]
	s_addc_u32 s93, s15, 0
	s_mov_b32 m0, s22
	s_nop 0
	global_load_lds_dwordx4 v130, s[92:93]
	s_add_u32 s83, s83, 0xb0000
	s_addc_u32 s82, s82, 0
	s_add_u32 s92, s83, s96
	s_addc_u32 s93, s82, s97
	s_add_u32 s96, s92, 0x58000
	s_mov_b32 m0, s23
	s_nop 0
	global_load_lds_dwordx4 v130, s[92:93]
	s_addc_u32 s97, s93, 0
	s_mov_b32 m0, s24
	s_nop 0
	global_load_lds_dwordx4 v130, s[96:97]
	s_waitcnt vmcnt(8) lgkmcnt(0)
	s_barrier
	s_waitcnt lgkmcnt(7)
	v_mfma_f32_16x16x32_bf16 v[60:63], v[142:145], v[178:181], v[60:63]
	v_mfma_f32_16x16x32_bf16 v[56:59], v[170:173], v[178:181], v[56:59]
	s_waitcnt lgkmcnt(5)
	v_mfma_f32_16x16x32_bf16 v[52:55], v[142:145], v[186:189], v[52:55]
	v_mfma_f32_16x16x32_bf16 v[48:51], v[170:173], v[186:189], v[48:51]
	s_waitcnt lgkmcnt(3)
	v_mfma_f32_16x16x32_bf16 v[44:47], v[142:145], v[194:197], v[44:47]
	v_mfma_f32_16x16x32_bf16 v[40:43], v[170:173], v[194:197], v[40:43]
	s_waitcnt lgkmcnt(1)
	v_mfma_f32_16x16x32_bf16 v[36:39], v[142:145], v[202:205], v[36:39]
	v_mfma_f32_16x16x32_bf16 v[32:35], v[170:173], v[202:205], v[32:35]
	v_mfma_f32_16x16x32_bf16 v[60:63], v[166:169], v[182:185], v[60:63]
	v_mfma_f32_16x16x32_bf16 v[56:59], v[174:177], v[182:185], v[56:59]
	v_mfma_f32_16x16x32_bf16 v[52:55], v[166:169], v[190:193], v[52:55]
	v_mfma_f32_16x16x32_bf16 v[48:51], v[174:177], v[190:193], v[48:51]
	v_mfma_f32_16x16x32_bf16 v[44:47], v[166:169], v[198:201], v[44:47]
	v_mfma_f32_16x16x32_bf16 v[40:43], v[174:177], v[198:201], v[40:43]
	s_waitcnt lgkmcnt(0)
	v_mfma_f32_16x16x32_bf16 v[36:39], v[166:169], v[206:209], v[36:39]
	v_mfma_f32_16x16x32_bf16 v[32:35], v[174:177], v[206:209], v[32:35]
	v_mfma_f32_16x16x32_bf16 v[28:31], v[210:213], v[178:181], v[28:31]
	v_mfma_f32_16x16x32_bf16 v[24:27], v[218:221], v[178:181], v[24:27]
	v_mfma_f32_16x16x32_bf16 v[20:23], v[210:213], v[186:189], v[20:23]
	v_mfma_f32_16x16x32_bf16 v[16:19], v[218:221], v[186:189], v[16:19]
	v_mfma_f32_16x16x32_bf16 v[12:15], v[210:213], v[194:197], v[12:15]
	v_mfma_f32_16x16x32_bf16 v[8:11], v[218:221], v[194:197], v[8:11]
	v_mfma_f32_16x16x32_bf16 v[4:7], v[210:213], v[202:205], v[4:7]
	v_mfma_f32_16x16x32_bf16 v[0:3], v[218:221], v[202:205], v[0:3]
	v_mfma_f32_16x16x32_bf16 v[28:31], v[214:217], v[182:185], v[28:31]
	v_mfma_f32_16x16x32_bf16 v[24:27], v[222:225], v[182:185], v[24:27]
	v_mfma_f32_16x16x32_bf16 v[20:23], v[214:217], v[190:193], v[20:23]
	v_mfma_f32_16x16x32_bf16 v[16:19], v[222:225], v[190:193], v[16:19]
	v_mfma_f32_16x16x32_bf16 v[12:15], v[214:217], v[198:201], v[12:15]
	v_mfma_f32_16x16x32_bf16 v[8:11], v[222:225], v[198:201], v[8:11]
	v_mfma_f32_16x16x32_bf16 v[4:7], v[214:217], v[206:209], v[4:7]
	v_mfma_f32_16x16x32_bf16 v[0:3], v[222:225], v[206:209], v[0:3]
	s_barrier
	ds_read_b128 v[142:145], v135 offset:32768
	ds_read_b128 v[166:169], v139 offset:32768
	ds_read_b128 v[170:173], v135 offset:34816
	ds_read_b128 v[174:177], v139 offset:34816
	ds_read_b128 v[178:181], v136 offset:32768
	ds_read_b128 v[182:185], v137 offset:32768
	ds_read_b128 v[186:189], v136 offset:34816
	ds_read_b128 v[190:193], v137 offset:34816
	ds_read_b128 v[194:197], v136 offset:36864
	ds_read_b128 v[198:201], v137 offset:36864
	ds_read_b128 v[202:205], v136 offset:38912
	ds_read_b128 v[206:209], v137 offset:38912
	s_add_u32 s92, s14, 0xb0000
	s_addc_u32 s93, s15, 0
	s_add_u32 s96, s14, 0x108000
	s_mov_b32 m0, s25
	s_nop 0
	global_load_lds_dwordx4 v130, s[92:93]
	s_addc_u32 s97, s15, 0
	s_mov_b32 m0, s26
	s_nop 0
	global_load_lds_dwordx4 v130, s[96:97]
	ds_read_b128 v[210:213], v135 offset:49152
	ds_read_b128 v[214:217], v139 offset:49152
	ds_read_b128 v[218:221], v135 offset:51200
	ds_read_b128 v[222:225], v139 offset:51200
	s_waitcnt vmcnt(8) lgkmcnt(0)
	s_barrier
	s_waitcnt lgkmcnt(7)
	v_mfma_f32_16x16x32_bf16 v[124:127], v[142:145], v[178:181], v[124:127]
	v_mfma_f32_16x16x32_bf16 v[120:123], v[170:173], v[178:181], v[120:123]
	s_waitcnt lgkmcnt(5)
	v_mfma_f32_16x16x32_bf16 v[116:119], v[142:145], v[186:189], v[116:119]
	v_mfma_f32_16x16x32_bf16 v[112:115], v[170:173], v[186:189], v[112:115]
	s_waitcnt lgkmcnt(3)
	v_mfma_f32_16x16x32_bf16 v[108:111], v[142:145], v[194:197], v[108:111]
	v_mfma_f32_16x16x32_bf16 v[104:107], v[170:173], v[194:197], v[104:107]
	s_waitcnt lgkmcnt(1)
	v_mfma_f32_16x16x32_bf16 v[100:103], v[142:145], v[202:205], v[100:103]
	v_mfma_f32_16x16x32_bf16 v[96:99], v[170:173], v[202:205], v[96:99]
	v_mfma_f32_16x16x32_bf16 v[124:127], v[166:169], v[182:185], v[124:127]
	v_mfma_f32_16x16x32_bf16 v[120:123], v[174:177], v[182:185], v[120:123]
	v_mfma_f32_16x16x32_bf16 v[116:119], v[166:169], v[190:193], v[116:119]
	v_mfma_f32_16x16x32_bf16 v[112:115], v[174:177], v[190:193], v[112:115]
	v_mfma_f32_16x16x32_bf16 v[108:111], v[166:169], v[198:201], v[108:111]
	v_mfma_f32_16x16x32_bf16 v[104:107], v[174:177], v[198:201], v[104:107]
	s_waitcnt lgkmcnt(0)
	v_mfma_f32_16x16x32_bf16 v[100:103], v[166:169], v[206:209], v[100:103]
	v_mfma_f32_16x16x32_bf16 v[96:99], v[174:177], v[206:209], v[96:99]
	s_waitcnt lgkmcnt(3)
	v_mfma_f32_16x16x32_bf16 v[92:95], v[210:213], v[178:181], v[92:95]
	s_waitcnt lgkmcnt(1)
	v_mfma_f32_16x16x32_bf16 v[88:91], v[218:221], v[178:181], v[88:91]
	v_mfma_f32_16x16x32_bf16 v[84:87], v[210:213], v[186:189], v[84:87]
	v_mfma_f32_16x16x32_bf16 v[80:83], v[218:221], v[186:189], v[80:83]
	v_mfma_f32_16x16x32_bf16 v[76:79], v[210:213], v[194:197], v[76:79]
	v_mfma_f32_16x16x32_bf16 v[72:75], v[218:221], v[194:197], v[72:75]
	v_mfma_f32_16x16x32_bf16 v[68:71], v[210:213], v[202:205], v[68:71]
	v_mfma_f32_16x16x32_bf16 v[64:67], v[218:221], v[202:205], v[64:67]
	v_mfma_f32_16x16x32_bf16 v[92:95], v[214:217], v[182:185], v[92:95]
	s_waitcnt lgkmcnt(0)
	v_mfma_f32_16x16x32_bf16 v[88:91], v[222:225], v[182:185], v[88:91]
	v_mfma_f32_16x16x32_bf16 v[84:87], v[214:217], v[190:193], v[84:87]
	v_mfma_f32_16x16x32_bf16 v[80:83], v[222:225], v[190:193], v[80:83]
	v_mfma_f32_16x16x32_bf16 v[76:79], v[214:217], v[198:201], v[76:79]
	v_mfma_f32_16x16x32_bf16 v[72:75], v[222:225], v[198:201], v[72:75]
	v_mfma_f32_16x16x32_bf16 v[68:71], v[214:217], v[206:209], v[68:71]
	v_mfma_f32_16x16x32_bf16 v[64:67], v[222:225], v[206:209], v[64:67]
	s_barrier
	s_or_b32 s70, s70, 64
	s_add_u32 s92, s12, 0x80
	s_addc_u32 s93, s13, 0
	s_add_u32 s12, s12, 0x58080
	s_mov_b32 m0, s27
	s_nop 0
	global_load_lds_dwordx4 v130, s[92:93]
	s_addc_u32 s13, s13, 0
	s_mov_b32 m0, s28
	s_nop 0
	global_load_lds_dwordx4 v130, s[12:13]
	ds_read_b128 v[178:181], v136 offset:49152
	ds_read_b128 v[182:185], v137 offset:49152
	ds_read_b128 v[186:189], v136 offset:51200
	ds_read_b128 v[190:193], v137 offset:51200
	ds_read_b128 v[194:197], v136 offset:53248
	ds_read_b128 v[198:201], v137 offset:53248
	ds_read_b128 v[202:205], v136 offset:55296
	ds_read_b128 v[206:209], v137 offset:55296
	s_add_u32 s12, s14, 0x80
	s_addc_u32 s13, s15, 0
	s_add_u32 s14, s14, 0x58080
	s_mov_b32 m0, s29
	s_nop 0
	global_load_lds_dwordx4 v130, s[12:13]
	s_addc_u32 s15, s15, 0
	s_mov_b32 m0, s30
	s_nop 0
	global_load_lds_dwordx4 v130, s[14:15]
	s_lshl_b64 s[12:13], s[70:71], 1
	s_add_u32 s12, s83, s12
	s_addc_u32 s13, s82, s13
	s_add_u32 s14, s12, 0x58000
	s_mov_b32 m0, s31
	s_nop 0
	global_load_lds_dwordx4 v130, s[12:13]
	s_addc_u32 s15, s13, 0
	s_mov_b32 m0, s34
	s_nop 0
	global_load_lds_dwordx4 v130, s[14:15]
	s_waitcnt vmcnt(8) lgkmcnt(0)
	s_barrier
	s_waitcnt lgkmcnt(7)
	v_mfma_f32_16x16x32_bf16 v[60:63], v[142:145], v[178:181], v[60:63]
	v_mfma_f32_16x16x32_bf16 v[56:59], v[170:173], v[178:181], v[56:59]
	s_waitcnt lgkmcnt(5)
	v_mfma_f32_16x16x32_bf16 v[52:55], v[142:145], v[186:189], v[52:55]
	v_mfma_f32_16x16x32_bf16 v[48:51], v[170:173], v[186:189], v[48:51]
	s_waitcnt lgkmcnt(3)
	v_mfma_f32_16x16x32_bf16 v[44:47], v[142:145], v[194:197], v[44:47]
	v_mfma_f32_16x16x32_bf16 v[40:43], v[170:173], v[194:197], v[40:43]
	s_waitcnt lgkmcnt(1)
	v_mfma_f32_16x16x32_bf16 v[36:39], v[142:145], v[202:205], v[36:39]
	v_mfma_f32_16x16x32_bf16 v[32:35], v[170:173], v[202:205], v[32:35]
	v_mfma_f32_16x16x32_bf16 v[60:63], v[166:169], v[182:185], v[60:63]
	v_mfma_f32_16x16x32_bf16 v[56:59], v[174:177], v[182:185], v[56:59]
	v_mfma_f32_16x16x32_bf16 v[52:55], v[166:169], v[190:193], v[52:55]
	v_mfma_f32_16x16x32_bf16 v[48:51], v[174:177], v[190:193], v[48:51]
	v_mfma_f32_16x16x32_bf16 v[44:47], v[166:169], v[198:201], v[44:47]
	v_mfma_f32_16x16x32_bf16 v[40:43], v[174:177], v[198:201], v[40:43]
	s_waitcnt lgkmcnt(0)
	v_mfma_f32_16x16x32_bf16 v[36:39], v[166:169], v[206:209], v[36:39]
	v_mfma_f32_16x16x32_bf16 v[32:35], v[174:177], v[206:209], v[32:35]
	v_mfma_f32_16x16x32_bf16 v[28:31], v[210:213], v[178:181], v[28:31]
	v_mfma_f32_16x16x32_bf16 v[24:27], v[218:221], v[178:181], v[24:27]
	v_mfma_f32_16x16x32_bf16 v[20:23], v[210:213], v[186:189], v[20:23]
	v_mfma_f32_16x16x32_bf16 v[16:19], v[218:221], v[186:189], v[16:19]
	v_mfma_f32_16x16x32_bf16 v[12:15], v[210:213], v[194:197], v[12:15]
	v_mfma_f32_16x16x32_bf16 v[8:11], v[218:221], v[194:197], v[8:11]
	v_mfma_f32_16x16x32_bf16 v[4:7], v[210:213], v[202:205], v[4:7]
	v_mfma_f32_16x16x32_bf16 v[0:3], v[218:221], v[202:205], v[0:3]
	v_mfma_f32_16x16x32_bf16 v[28:31], v[214:217], v[182:185], v[28:31]
	v_mfma_f32_16x16x32_bf16 v[24:27], v[222:225], v[182:185], v[24:27]
	v_mfma_f32_16x16x32_bf16 v[20:23], v[214:217], v[190:193], v[20:23]
	v_mfma_f32_16x16x32_bf16 v[16:19], v[222:225], v[190:193], v[16:19]
	v_mfma_f32_16x16x32_bf16 v[12:15], v[214:217], v[198:201], v[12:15]
	v_mfma_f32_16x16x32_bf16 v[8:11], v[222:225], v[198:201], v[8:11]
	v_mfma_f32_16x16x32_bf16 v[4:7], v[214:217], v[206:209], v[4:7]
	v_mfma_f32_16x16x32_bf16 v[0:3], v[222:225], v[206:209], v[0:3]
	s_add_i32 s89, s89, 2
	s_addk_i32 s94, 0x80
	s_add_u32 s10, s10, 0x100
	s_addc_u32 s11, s11, 0
	s_cmp_gt_u32 s89, 41
	s_barrier
	s_cbranch_scc0 .LBB0_220
; #define WAIT_V(n) asm volatile("s_waitcnt vmcnt(" #n ")" ::: "memory")
; #define BAR __builtin_amdgcn_s_barrier()
; template <int N, int K, int EPI>
; __device__ void gemm_phase(const u16* __restrict__ A, const u16* __restrict__ Bt, const EpiArgs ea, char* smem, int tid) {
;     ...
;         u16* f = ea.o0;
; #pragma unroll
;         for (int ai = 0; ai < 2; ++ai)
; #pragma unroll
;           for (int bj = 0; bj < 2; ++bj)
; #pragma unroll
;             for (int m = 0; m < 4; ++m) {
;               const int row = brow + ai * HALF + wr * 64 + m * 16 + fr_e;
;               const int col = pn * BM + bj * HALF + wc * 32 + fq_e * 8;
;               const f32x4 v0 = acc[ai][bj][m][0], v1 = acc[ai][bj][m][1];
;               u32x4 o = {pk_bf16(v0[0], v0[1]), pk_bf16(v0[2], v0[3]), pk_bf16(v1[0], v1[1]), pk_bf16(v1[2], v1[3])};
;               *(u32x4*)(f + (size_t)row * N + col) = o;
;             }
;     ...
;     if (!has_next) break;
; #pragma unroll
;     for (int ai = 0; ai < 2; ++ai)
; #pragma unroll
;       for (int bj = 0; bj < 2; ++bj)
; #pragma unroll
;         for (int m = 0; m < 4; ++m)
; #pragma unroll
;           for (int n = 0; n < 2; ++n) acc[ai][bj][m][n] = f32x4{0.f, 0.f, 0.f, 0.f};
;     v = vn; pm = pmn; pn = pnn; Ab = Abn; Bb = Bbn;
;   }
;   WAIT_V(0);
;   if (wr == 0) BAR;
	s_lshl_b32 s6, s88, 8
	v_mov_b32_e32 v128, v131
	v_mov_b32_e32 v129, v132
	s_add_i32 s6, s6, s35
	v_cvt_pk_bf16_f32 v124, v124, v125
	v_cvt_pk_bf16_f32 v125, v126, v127
	v_cvt_pk_bf16_f32 v126, v120, v121
	v_cvt_pk_bf16_f32 v127, v122, v123
	v_cvt_pk_bf16_f32 v116, v116, v117
	s_nop 0
	v_add_u32_e32 v142, s6, v128
	s_lshl_b32 s6, s73, 8
	s_or_b32 s6, s6, s42
	v_lshl_add_u32 v144, v129, 3, s6
	v_ashrrev_i32_e32 v145, 31, v144
	v_ashrrev_i32_e32 v143, 31, v142
	v_lshl_add_u64 v[128:129], v[144:145], 1, s[64:65]
	v_lshlrev_b64 v[120:121], 11, v[142:143]
	v_lshl_add_u64 v[122:123], v[128:129], 0, v[120:121]
	global_store_dwordx4 v[122:123], v[124:127], off
	v_add_u32_e32 v122, 16, v142
	v_ashrrev_i32_e32 v123, 31, v122
	v_cvt_pk_bf16_f32 v117, v118, v119
	v_cvt_pk_bf16_f32 v118, v112, v113
	v_lshlrev_b64 v[112:113], 11, v[122:123]
	v_cvt_pk_bf16_f32 v119, v114, v115
	v_lshl_add_u64 v[114:115], v[128:129], 0, v[112:113]
	global_store_dwordx4 v[114:115], v[116:119], off
	v_add_u32_e32 v114, 32, v142
	v_ashrrev_i32_e32 v115, 31, v114
	v_cvt_pk_bf16_f32 v108, v108, v109
	v_cvt_pk_bf16_f32 v109, v110, v111
	v_cvt_pk_bf16_f32 v110, v104, v105
	v_lshlrev_b64 v[104:105], 11, v[114:115]
	v_cvt_pk_bf16_f32 v111, v106, v107
	v_lshl_add_u64 v[106:107], v[128:129], 0, v[104:105]
	global_store_dwordx4 v[106:107], v[108:111], off
	v_add_u32_e32 v106, 48, v142
	v_ashrrev_i32_e32 v107, 31, v106
	v_cvt_pk_bf16_f32 v100, v100, v101
	v_cvt_pk_bf16_f32 v101, v102, v103
	v_cvt_pk_bf16_f32 v102, v96, v97
	v_lshlrev_b64 v[96:97], 11, v[106:107]
	v_cvt_pk_bf16_f32 v103, v98, v99
	v_lshl_add_u64 v[98:99], v[128:129], 0, v[96:97]
	global_store_dwordx4 v[98:99], v[100:103], off
	v_add_u32_e32 v98, 0x80, v144
	v_ashrrev_i32_e32 v99, 31, v98
	v_lshl_add_u64 v[98:99], v[98:99], 1, s[64:65]
	v_cvt_pk_bf16_f32 v68, v68, v69
	v_cvt_pk_bf16_f32 v69, v70, v71
	v_cvt_pk_bf16_f32 v70, v64, v65
	v_lshl_add_u64 v[64:65], v[98:99], 0, v[96:97]
	v_cvt_pk_bf16_f32 v71, v66, v67
	global_store_dwordx4 v[64:65], v[68:71], off
	v_add_u32_e32 v64, 0x80, v142
	v_ashrrev_i32_e32 v65, 31, v64
	v_cvt_pk_bf16_f32 v60, v60, v61
	v_cvt_pk_bf16_f32 v61, v62, v63
	v_cvt_pk_bf16_f32 v62, v56, v57
	v_lshlrev_b64 v[56:57], 11, v[64:65]
	v_cvt_pk_bf16_f32 v92, v92, v93
	v_cvt_pk_bf16_f32 v93, v94, v95
	v_cvt_pk_bf16_f32 v94, v88, v89
	v_lshl_add_u64 v[88:89], v[98:99], 0, v[120:121]
	v_cvt_pk_bf16_f32 v84, v84, v85
	v_cvt_pk_bf16_f32 v85, v86, v87
	v_cvt_pk_bf16_f32 v86, v80, v81
	v_lshl_add_u64 v[80:81], v[98:99], 0, v[112:113]
	v_cvt_pk_bf16_f32 v76, v76, v77
	v_cvt_pk_bf16_f32 v77, v78, v79
	v_cvt_pk_bf16_f32 v78, v72, v73
	v_lshl_add_u64 v[72:73], v[98:99], 0, v[104:105]
	v_cvt_pk_bf16_f32 v63, v58, v59
	v_lshl_add_u64 v[58:59], v[128:129], 0, v[56:57]
	v_cvt_pk_bf16_f32 v95, v90, v91
	global_store_dwordx4 v[88:89], v[92:95], off
	v_cvt_pk_bf16_f32 v87, v82, v83
	global_store_dwordx4 v[80:81], v[84:87], off
	v_cvt_pk_bf16_f32 v79, v74, v75
	global_store_dwordx4 v[72:73], v[76:79], off
	global_store_dwordx4 v[58:59], v[60:63], off
	v_add_u32_e32 v58, 0x90, v142
	v_ashrrev_i32_e32 v59, 31, v58
	v_cvt_pk_bf16_f32 v52, v52, v53
	v_cvt_pk_bf16_f32 v53, v54, v55
	v_cvt_pk_bf16_f32 v54, v48, v49
	v_lshlrev_b64 v[48:49], 11, v[58:59]
	v_cvt_pk_bf16_f32 v55, v50, v51
	v_lshl_add_u64 v[50:51], v[128:129], 0, v[48:49]
	global_store_dwordx4 v[50:51], v[52:55], off
	v_add_u32_e32 v50, 0xa0, v142
	v_ashrrev_i32_e32 v51, 31, v50
	v_cvt_pk_bf16_f32 v44, v44, v45
	v_cvt_pk_bf16_f32 v45, v46, v47
	v_cvt_pk_bf16_f32 v46, v40, v41
	v_lshlrev_b64 v[40:41], 11, v[50:51]
	v_cvt_pk_bf16_f32 v47, v42, v43
	v_lshl_add_u64 v[42:43], v[128:129], 0, v[40:41]
	global_store_dwordx4 v[42:43], v[44:47], off
	v_add_u32_e32 v42, 0xb0, v142
	v_ashrrev_i32_e32 v43, 31, v42
	v_cvt_pk_bf16_f32 v36, v36, v37
	v_cvt_pk_bf16_f32 v37, v38, v39
	v_cvt_pk_bf16_f32 v38, v32, v33
	v_lshlrev_b64 v[32:33], 11, v[42:43]
	v_cvt_pk_bf16_f32 v39, v34, v35
	v_lshl_add_u64 v[34:35], v[128:129], 0, v[32:33]
	v_cvt_pk_bf16_f32 v28, v28, v29
	v_cvt_pk_bf16_f32 v29, v30, v31
	v_cvt_pk_bf16_f32 v30, v24, v25
	v_lshl_add_u64 v[24:25], v[98:99], 0, v[56:57]
	v_cvt_pk_bf16_f32 v20, v20, v21
	v_cvt_pk_bf16_f32 v21, v22, v23
	v_cvt_pk_bf16_f32 v22, v16, v17
	v_lshl_add_u64 v[16:17], v[98:99], 0, v[48:49]
	v_cvt_pk_bf16_f32 v12, v12, v13
	v_cvt_pk_bf16_f32 v13, v14, v15
	v_cvt_pk_bf16_f32 v14, v8, v9
	v_lshl_add_u64 v[8:9], v[98:99], 0, v[40:41]
	v_cvt_pk_bf16_f32 v4, v4, v5
	v_cvt_pk_bf16_f32 v5, v6, v7
	v_cvt_pk_bf16_f32 v6, v0, v1
	v_lshl_add_u64 v[0:1], v[98:99], 0, v[32:33]
	s_and_b64 vcc, exec, s[0:1]
	s_mov_b32 s88, s67
	s_mov_b32 s73, s72
	s_mov_b64 s[8:9], s[4:5]
	s_mov_b64 s[6:7], s[2:3]
	global_store_dwordx4 v[34:35], v[36:39], off
	v_cvt_pk_bf16_f32 v31, v26, v27
	global_store_dwordx4 v[24:25], v[28:31], off
	v_cvt_pk_bf16_f32 v23, v18, v19
	global_store_dwordx4 v[16:17], v[20:23], off
	v_cvt_pk_bf16_f32 v15, v10, v11
	global_store_dwordx4 v[8:9], v[12:15], off
	v_cvt_pk_bf16_f32 v7, v2, v3
	global_store_dwordx4 v[0:1], v[4:7], off
	s_cbranch_vccz .LBB0_217
	s_setprio 0
	s_waitcnt vmcnt(0)
	v_readlane_b32 s34, v226, 32
	v_readlane_b32 s36, v226, 30
	s_cmpk_gt_u32 s18, 0xff
	s_movk_i32 s27, 0x7fff
	s_mov_b32 s28, 0x800000
	s_mov_b32 s29, 0xa000000
	s_mov_b32 s30, 0x41000
	v_readlane_b32 s35, v226, 33
	v_readlane_b32 s37, v226, 31
	s_cbranch_scc1 .LBB0_224
	s_barrier

; #define WAIT_V(n) asm volatile("s_waitcnt vmcnt(" #n ")" ::: "memory")
; #define BAR __builtin_amdgcn_s_barrier()
; template <int N, int K, int EPI>
; __device__ void gemm_phase(const u16* __restrict__ A, const u16* __restrict__ Bt, const EpiArgs ea, char* smem, int tid) {
;     ...
;   int tidl = tid;
;   asm volatile("" : "+v"(tidl));
;   const int wid = __builtin_amdgcn_readfirstlane(tidl >> 6);
;   const int lane = tidl & 63, wr = wid >> 2, wc = wid & 3, fr = lane & 15, fq = lane >> 4;
;   const int tb = tidl * 16;
;   unsigned off0b;
;   { int R, C; stage_rc((tidl & 63) * 16 + wid * 1024, R, C); off0b = (unsigned)(R * K + C) * 2u; }
;   const unsigned lds0 = (unsigned)(size_t)(__attribute__((address_space(3))) char*)smem;
;   int pm, pn; tile_map(v, nN, pm, pn);
;   const u16* Ab = A + (size_t)pm * BM * K;
;   const u16* Bb = Bt + (size_t)pn * BM * K;
;   f32x4 acc[2][2][4][2] = {};
;   bf16x8 At[4][2], B0[2][2], B1[2][2];
;   STAGE(SB(0, 0), GP(Bb, 0, 0)); STAGE(SA(0, 0), GP(Ab, 0, 0));
;   STAGE(SB(0, 1), GP(Bb, 1, 0)); STAGE(SA(0, 1), GP(Ab, 1, 0));
;   if (wr == 1) BAR;
;   WAIT_V(4); BAR;
;   STAGE(SB(1, 0), GP(Bb, 0, 1)); STAGE(SA(1, 0), GP(Ab, 0, 1)); STAGE(SB(1, 1), GP(Bb, 1, 1));
;   WAIT_V(6); BAR;
;   while (true) {
;     const int vn = v + gridDim.x;
;     const bool has_next = vn < nwg;
;     int pmn = pm, pnn = pn;
;     if (has_next) tile_map(vn, nN, pmn, pnn);
;     const u16* Abn = A + (size_t)pmn * BM * K;
;     const u16* Bbn = Bt + (size_t)pnn * BM * K;
.LBB0_232:
	s_and_b32 s18, s2, 3
	s_add_u32 s2, s12, 0x80
	s_addc_u32 s3, s13, 0
	s_add_u32 s4, s12, 0x20080
	s_addc_u32 s5, s13, 0
	s_add_u32 s6, s10, 0x80
	s_addc_u32 s7, s11, 0
	s_add_u32 s8, s10, 0x20080
	s_addc_u32 s9, s11, 0
	s_add_u32 s14, s12, 0x40080
	s_addc_u32 s15, s13, 0
	s_add_u32 s16, s12, 0x60080
	v_readlane_b32 s19, v227, 60
	s_addc_u32 s17, s13, 0
	s_waitcnt vmcnt(2)
	s_barrier
	s_add_i32 s31, s1, s19
	s_mov_b32 m0, s31
	s_nop 0
	global_load_lds_dwordx4 v130, s[2:3]
	v_and_b32_e32 v131, 15, v0
	s_add_i32 s34, s23, 0x1a000
	s_mov_b32 m0, s34
	s_nop 0
	global_load_lds_dwordx4 v130, s[4:5]
	v_lshlrev_b32_e32 v3, 2, v0
	v_lshrrev_b32_e32 v132, 4, v1
	s_add_i32 s35, s23, 0x8000
	s_mov_b32 m0, s35
	s_nop 0
	global_load_lds_dwordx4 v130, s[6:7]
	v_and_b32_e32 v1, 48, v0
	v_lshlrev_b32_e32 v2, 6, v131
	v_and_b32_e32 v3, 32, v3
	s_add_i32 s36, s23, 0xa000
	s_mov_b32 m0, s36
	s_nop 0
	global_load_lds_dwordx4 v130, s[8:9]
	v_readlane_b32 s3, v227, 61
	v_bitop3_b32 v2, v2, v3, v1 bitop3:0x36
	s_add_i32 s2, 0, 0x10000
	s_add_i32 s37, s1, s3
	s_mov_b32 m0, s37
	s_nop 0
	global_load_lds_dwordx4 v130, s[14:15]
	v_add_u32_e32 v4, s2, v2
	s_add_i32 s2, 0, 0x14000
	s_add_i32 s42, s23, 0x1e000
	s_mov_b32 m0, s42
	s_nop 0
	global_load_lds_dwordx4 v130, s[16:17]
	v_add_u32_e32 v5, s2, v2
	v_lshlrev_b32_e32 v0, 6, v0
	s_movk_i32 s2, 0x3c0
	s_waitcnt vmcnt(6)
	s_lshl_b32 s1, s18, 12
	s_lshl_b32 s43, s0, 6
	v_add_u32_e32 v6, s19, v2
	v_add_u32_e32 v7, s3, v2
	s_lshl_b32 s0, s0, 13
	v_add_u32_e32 v2, 0, v2
	v_and_or_b32 v0, v0, s2, v1
	v_xad_u32 v134, v0, v3, 0
	s_or_b32 s67, s0, 0x800
	s_or_b32 s2, s0, 0x1000
	s_or_b32 s3, s0, 0x1800
	v_add_u32_e32 v135, s1, v4
	v_add_u32_e32 v136, s0, v2
	v_add_u32_e32 v139, s1, v5
	v_add_u32_e32 v140, s1, v6
	v_add_u32_e32 v141, s1, v7
	v_readlane_b32 s0, v227, 31
	s_add_i32 s64, s23, 0xc000
	s_add_i32 s65, s23, 0xe000
	s_lshl_b32 s66, s18, 5
	v_add_u32_e32 v137, s2, v134
	v_add_u32_e32 v138, s3, v134
	s_mov_b32 s77, s0
	v_readlane_b32 s73, v227, 30
	s_mov_b32 s72, s94
	s_barrier
	v_readlane_b32 s1, v227, 32
	v_and_b32_e32 v120, 15, v164
	v_bfe_u32 v121, v164, 4, 2
	v_lshrrev_b32_e32 v122, 3, v120
	v_and_b32_e32 v123, 7, v120
	v_lshlrev_b32_e32 v124, 10, v122
	v_lshl_add_u32 v124, v123, 7, v124
	v_lshl_add_u32 v124, v122, 6, v124
	v_bfe_u32 v125, v120, 1, 2
	v_xor_b32_e32 v125, v125, v121
	v_lshl_add_u32 v124, v125, 4, v124
	v_lshrrev_b32_e32 v126, 8, v164
	v_lshl_add_u32 v136, v126, 13, v124
	v_xor_b32_e32 v137, 64, v136
	v_bfe_u32 v126, v164, 6, 2
	v_lshl_add_u32 v126, v126, 12, v124
	v_add_u32_e32 v135, 0x10000, v126
	v_xor_b32_e32 v139, 64, v135
	v_readfirstlane_b32 s100, v164
	s_lshr_b32 s100, s100, 8
	s_cmp_eq_u32 s100, 1
	s_cbranch_scc0 .Lsp_gu
	s_setprio 1
.Lsp_gu:
.LBB0_233:
	s_add_i32 s72, s72, s33
	s_cmpk_gt_i32 s72, 0xaff
	s_cselect_b64 s[0:1], -1, 0
	s_and_b64 vcc, exec, s[0:1]
	s_mov_b32 s2, s77
	s_mov_b32 s4, s73
	s_cbranch_vccnz .LBB0_235
	s_and_b32 s2, s72, 7
	s_ashr_i32 s3, s72, 3
	s_mulk_i32 s2, 0x160
	s_add_i32 s2, s2, s3
	s_mul_hi_i32 s3, s2, 0x2e8ba2e9
	s_lshr_b32 s4, s3, 31
	s_ashr_i32 s3, s3, 5
	s_add_i32 s3, s3, s4
	s_lshl_b32 s4, s3, 3
	s_mulk_i32 s3, 0xb0
	s_sub_i32 s2, s2, s3
	s_bfe_u32 s3, s2, 0x3001c
	s_add_i32 s3, s2, s3
	s_sext_i32_i16 s5, s3
	s_and_b32 s3, s3, 0xfff8
	s_sub_i32 s2, s2, s3
	s_sext_i32_i16 s2, s2
	s_add_i32 s2, s4, s2
	s_ashr_i32 s4, s5, 3

.LBB0_236:
	ds_read_b128 v[142:145], v135
	ds_read_b128 v[166:169], v139
	ds_read_b128 v[170:173], v135 offset:2048
	ds_read_b128 v[174:177], v139 offset:2048
	s_add_u32 s16, s14, 0x40080
	s_addc_u32 s17, s15, 0
	s_add_u32 s18, s14, 0x60080
	s_addc_u32 s19, s15, 0
	s_cmp_eq_u32 s3, 12
	s_cselect_b32 s82, s9, s13
	s_cselect_b32 s83, s8, s12
	s_cselect_b32 s92, s7, s11
	s_cselect_b32 s93, s6, s10
	s_nop 0
	ds_read_b128 v[178:181], v136
	ds_read_b128 v[182:185], v137
	ds_read_b128 v[186:189], v136 offset:2048
	ds_read_b128 v[190:193], v137 offset:2048
	ds_read_b128 v[194:197], v136 offset:4096
	ds_read_b128 v[198:201], v137 offset:4096
	ds_read_b128 v[202:205], v136 offset:6144
	ds_read_b128 v[206:209], v137 offset:6144
	s_mov_b32 m0, s64
	s_nop 0
	global_load_lds_dwordx4 v130, s[16:17]
	s_nop 0
	s_mov_b32 m0, s65
	s_nop 0
	global_load_lds_dwordx4 v130, s[18:19]
	ds_read_b128 v[210:213], v135 offset:16384
	ds_read_b128 v[214:217], v139 offset:16384
	ds_read_b128 v[218:221], v135 offset:18432
	ds_read_b128 v[222:225], v139 offset:18432
	s_waitcnt vmcnt(8) lgkmcnt(0)
	s_barrier
	s_waitcnt lgkmcnt(7)
	v_mfma_f32_16x16x32_bf16 v[124:127], v[142:145], v[178:181], v[124:127]
	v_mfma_f32_16x16x32_bf16 v[116:119], v[170:173], v[178:181], v[116:119]
	s_waitcnt lgkmcnt(5)
	v_mfma_f32_16x16x32_bf16 v[108:111], v[142:145], v[186:189], v[108:111]
	v_mfma_f32_16x16x32_bf16 v[100:103], v[170:173], v[186:189], v[100:103]
	s_waitcnt lgkmcnt(3)
	v_mfma_f32_16x16x32_bf16 v[92:95], v[142:145], v[194:197], v[92:95]
	v_mfma_f32_16x16x32_bf16 v[84:87], v[170:173], v[194:197], v[84:87]
	s_waitcnt lgkmcnt(1)
	v_mfma_f32_16x16x32_bf16 v[76:79], v[142:145], v[202:205], v[76:79]
	v_mfma_f32_16x16x32_bf16 v[68:71], v[170:173], v[202:205], v[68:71]
	v_mfma_f32_16x16x32_bf16 v[124:127], v[166:169], v[182:185], v[124:127]
	v_mfma_f32_16x16x32_bf16 v[116:119], v[174:177], v[182:185], v[116:119]
	v_mfma_f32_16x16x32_bf16 v[108:111], v[166:169], v[190:193], v[108:111]
	v_mfma_f32_16x16x32_bf16 v[100:103], v[174:177], v[190:193], v[100:103]
	v_mfma_f32_16x16x32_bf16 v[92:95], v[166:169], v[198:201], v[92:95]
	v_mfma_f32_16x16x32_bf16 v[84:87], v[174:177], v[198:201], v[84:87]
	s_waitcnt lgkmcnt(0)
	v_mfma_f32_16x16x32_bf16 v[76:79], v[166:169], v[206:209], v[76:79]
	v_mfma_f32_16x16x32_bf16 v[68:71], v[174:177], v[206:209], v[68:71]
	s_waitcnt lgkmcnt(3)
	v_mfma_f32_16x16x32_bf16 v[120:123], v[210:213], v[178:181], v[120:123]
	s_waitcnt lgkmcnt(1)
	v_mfma_f32_16x16x32_bf16 v[112:115], v[218:221], v[178:181], v[112:115]
	v_mfma_f32_16x16x32_bf16 v[104:107], v[210:213], v[186:189], v[104:107]
	v_mfma_f32_16x16x32_bf16 v[96:99], v[218:221], v[186:189], v[96:99]
	v_mfma_f32_16x16x32_bf16 v[88:91], v[210:213], v[194:197], v[88:91]
	v_mfma_f32_16x16x32_bf16 v[80:83], v[218:221], v[194:197], v[80:83]
	v_mfma_f32_16x16x32_bf16 v[72:75], v[210:213], v[202:205], v[72:75]
	v_mfma_f32_16x16x32_bf16 v[64:67], v[218:221], v[202:205], v[64:67]
	v_mfma_f32_16x16x32_bf16 v[120:123], v[214:217], v[182:185], v[120:123]
	s_waitcnt lgkmcnt(0)
	v_mfma_f32_16x16x32_bf16 v[112:115], v[222:225], v[182:185], v[112:115]
	v_mfma_f32_16x16x32_bf16 v[104:107], v[214:217], v[190:193], v[104:107]
	v_mfma_f32_16x16x32_bf16 v[96:99], v[222:225], v[190:193], v[96:99]
	v_mfma_f32_16x16x32_bf16 v[88:91], v[214:217], v[198:201], v[88:91]
	v_mfma_f32_16x16x32_bf16 v[80:83], v[222:225], v[198:201], v[80:83]
	v_mfma_f32_16x16x32_bf16 v[72:75], v[214:217], v[206:209], v[72:75]
	v_mfma_f32_16x16x32_bf16 v[64:67], v[222:225], v[206:209], v[64:67]
	s_barrier
	s_cselect_b32 s70, 0, s5
	s_lshl_b64 s[88:89], s[70:71], 1
	s_add_u32 s16, s83, s88
	s_addc_u32 s17, s82, s89
	s_add_u32 s18, s16, 0x20000
	s_mov_b32 m0, s24
	s_nop 0
	global_load_lds_dwordx4 v130, s[16:17]
	s_addc_u32 s19, s17, 0
	s_mov_b32 m0, s25
	s_nop 0
	global_load_lds_dwordx4 v130, s[18:19]
	ds_read_b128 v[178:181], v136 offset:16384
	ds_read_b128 v[182:185], v137 offset:16384
	ds_read_b128 v[186:189], v136 offset:18432
	ds_read_b128 v[190:193], v137 offset:18432
	ds_read_b128 v[194:197], v136 offset:20480
	ds_read_b128 v[198:201], v137 offset:20480
	ds_read_b128 v[202:205], v136 offset:22528
	ds_read_b128 v[206:209], v137 offset:22528
	s_add_u32 s18, s93, s88
	s_addc_u32 s19, s92, s89
	s_add_u32 s94, s18, 0x20000
	s_mov_b32 m0, s23
	s_nop 0
	global_load_lds_dwordx4 v130, s[18:19]
	s_addc_u32 s95, s19, 0
	s_mov_b32 m0, s26
	s_nop 0
	global_load_lds_dwordx4 v130, s[94:95]
	s_add_u32 s83, s83, 0x40000
	s_addc_u32 s82, s82, 0
	s_add_u32 s88, s83, s88
	s_addc_u32 s89, s82, s89
	s_add_u32 s94, s88, 0x20000
	s_mov_b32 m0, s27
	s_nop 0
	global_load_lds_dwordx4 v130, s[88:89]
	s_addc_u32 s95, s89, 0
	s_mov_b32 m0, s28
	s_nop 0
	global_load_lds_dwordx4 v130, s[94:95]
	s_waitcnt vmcnt(8) lgkmcnt(0)
	s_barrier
	s_waitcnt lgkmcnt(7)
	v_mfma_f32_16x16x32_bf16 v[60:63], v[142:145], v[178:181], v[60:63]
	v_mfma_f32_16x16x32_bf16 v[52:55], v[170:173], v[178:181], v[52:55]
	s_waitcnt lgkmcnt(5)
	v_mfma_f32_16x16x32_bf16 v[44:47], v[142:145], v[186:189], v[44:47]
	v_mfma_f32_16x16x32_bf16 v[36:39], v[170:173], v[186:189], v[36:39]
	s_waitcnt lgkmcnt(3)
	v_mfma_f32_16x16x32_bf16 v[28:31], v[142:145], v[194:197], v[28:31]
	v_mfma_f32_16x16x32_bf16 v[20:23], v[170:173], v[194:197], v[20:23]
	s_waitcnt lgkmcnt(1)
	v_mfma_f32_16x16x32_bf16 v[12:15], v[142:145], v[202:205], v[12:15]
	v_mfma_f32_16x16x32_bf16 v[4:7], v[170:173], v[202:205], v[4:7]
	v_mfma_f32_16x16x32_bf16 v[60:63], v[166:169], v[182:185], v[60:63]
	v_mfma_f32_16x16x32_bf16 v[52:55], v[174:177], v[182:185], v[52:55]
	v_mfma_f32_16x16x32_bf16 v[44:47], v[166:169], v[190:193], v[44:47]
	v_mfma_f32_16x16x32_bf16 v[36:39], v[174:177], v[190:193], v[36:39]
	v_mfma_f32_16x16x32_bf16 v[28:31], v[166:169], v[198:201], v[28:31]
	v_mfma_f32_16x16x32_bf16 v[20:23], v[174:177], v[198:201], v[20:23]
	s_waitcnt lgkmcnt(0)
	v_mfma_f32_16x16x32_bf16 v[12:15], v[166:169], v[206:209], v[12:15]
	v_mfma_f32_16x16x32_bf16 v[4:7], v[174:177], v[206:209], v[4:7]
	v_mfma_f32_16x16x32_bf16 v[56:59], v[210:213], v[178:181], v[56:59]
	v_mfma_f32_16x16x32_bf16 v[48:51], v[218:221], v[178:181], v[48:51]
	v_mfma_f32_16x16x32_bf16 v[40:43], v[210:213], v[186:189], v[40:43]
	v_mfma_f32_16x16x32_bf16 v[32:35], v[218:221], v[186:189], v[32:35]
	v_mfma_f32_16x16x32_bf16 v[24:27], v[210:213], v[194:197], v[24:27]
	v_mfma_f32_16x16x32_bf16 v[16:19], v[218:221], v[194:197], v[16:19]
	v_mfma_f32_16x16x32_bf16 v[8:11], v[210:213], v[202:205], v[8:11]
	v_mfma_f32_16x16x32_bf16 v[0:3], v[218:221], v[202:205], v[0:3]
	v_mfma_f32_16x16x32_bf16 v[56:59], v[214:217], v[182:185], v[56:59]
	v_mfma_f32_16x16x32_bf16 v[48:51], v[222:225], v[182:185], v[48:51]
	v_mfma_f32_16x16x32_bf16 v[40:43], v[214:217], v[190:193], v[40:43]
	v_mfma_f32_16x16x32_bf16 v[32:35], v[222:225], v[190:193], v[32:35]
	v_mfma_f32_16x16x32_bf16 v[24:27], v[214:217], v[198:201], v[24:27]
	v_mfma_f32_16x16x32_bf16 v[16:19], v[222:225], v[198:201], v[16:19]
	v_mfma_f32_16x16x32_bf16 v[8:11], v[214:217], v[206:209], v[8:11]
	v_mfma_f32_16x16x32_bf16 v[0:3], v[222:225], v[206:209], v[0:3]
	s_barrier
	ds_read_b128 v[142:145], v135 offset:32768
	ds_read_b128 v[166:169], v139 offset:32768
	ds_read_b128 v[170:173], v135 offset:34816
	ds_read_b128 v[174:177], v139 offset:34816
	ds_read_b128 v[178:181], v136 offset:32768
	ds_read_b128 v[182:185], v137 offset:32768
	ds_read_b128 v[186:189], v136 offset:34816
	ds_read_b128 v[190:193], v137 offset:34816
	ds_read_b128 v[194:197], v136 offset:36864
	ds_read_b128 v[198:201], v137 offset:36864
	ds_read_b128 v[202:205], v136 offset:38912
	ds_read_b128 v[206:209], v137 offset:38912
	s_add_u32 s88, s18, 0x40000
	s_addc_u32 s89, s19, 0
	s_add_u32 s94, s18, 0x60000
	s_mov_b32 m0, s29
	s_nop 0
	global_load_lds_dwordx4 v130, s[88:89]
	s_addc_u32 s95, s19, 0
	s_mov_b32 m0, s30
	s_nop 0
	global_load_lds_dwordx4 v130, s[94:95]
	ds_read_b128 v[210:213], v135 offset:49152
	ds_read_b128 v[214:217], v139 offset:49152
	ds_read_b128 v[218:221], v135 offset:51200
	ds_read_b128 v[222:225], v139 offset:51200
	s_waitcnt vmcnt(8) lgkmcnt(0)
	s_barrier
	s_waitcnt lgkmcnt(7)
	v_mfma_f32_16x16x32_bf16 v[124:127], v[142:145], v[178:181], v[124:127]
	v_mfma_f32_16x16x32_bf16 v[116:119], v[170:173], v[178:181], v[116:119]
	s_waitcnt lgkmcnt(5)
	v_mfma_f32_16x16x32_bf16 v[108:111], v[142:145], v[186:189], v[108:111]
	v_mfma_f32_16x16x32_bf16 v[100:103], v[170:173], v[186:189], v[100:103]
	s_waitcnt lgkmcnt(3)
	v_mfma_f32_16x16x32_bf16 v[92:95], v[142:145], v[194:197], v[92:95]
	v_mfma_f32_16x16x32_bf16 v[84:87], v[170:173], v[194:197], v[84:87]
	s_waitcnt lgkmcnt(1)
	v_mfma_f32_16x16x32_bf16 v[76:79], v[142:145], v[202:205], v[76:79]
	v_mfma_f32_16x16x32_bf16 v[68:71], v[170:173], v[202:205], v[68:71]
	v_mfma_f32_16x16x32_bf16 v[124:127], v[166:169], v[182:185], v[124:127]
	v_mfma_f32_16x16x32_bf16 v[116:119], v[174:177], v[182:185], v[116:119]
	v_mfma_f32_16x16x32_bf16 v[108:111], v[166:169], v[190:193], v[108:111]
	v_mfma_f32_16x16x32_bf16 v[100:103], v[174:177], v[190:193], v[100:103]
	v_mfma_f32_16x16x32_bf16 v[92:95], v[166:169], v[198:201], v[92:95]
	v_mfma_f32_16x16x32_bf16 v[84:87], v[174:177], v[198:201], v[84:87]
	s_waitcnt lgkmcnt(0)
	v_mfma_f32_16x16x32_bf16 v[76:79], v[166:169], v[206:209], v[76:79]
	v_mfma_f32_16x16x32_bf16 v[68:71], v[174:177], v[206:209], v[68:71]
	s_waitcnt lgkmcnt(3)
	v_mfma_f32_16x16x32_bf16 v[120:123], v[210:213], v[178:181], v[120:123]
	s_waitcnt lgkmcnt(1)
	v_mfma_f32_16x16x32_bf16 v[112:115], v[218:221], v[178:181], v[112:115]
	v_mfma_f32_16x16x32_bf16 v[104:107], v[210:213], v[186:189], v[104:107]
	v_mfma_f32_16x16x32_bf16 v[96:99], v[218:221], v[186:189], v[96:99]
	v_mfma_f32_16x16x32_bf16 v[88:91], v[210:213], v[194:197], v[88:91]
	v_mfma_f32_16x16x32_bf16 v[80:83], v[218:221], v[194:197], v[80:83]
	v_mfma_f32_16x16x32_bf16 v[72:75], v[210:213], v[202:205], v[72:75]
	v_mfma_f32_16x16x32_bf16 v[64:67], v[218:221], v[202:205], v[64:67]
	v_mfma_f32_16x16x32_bf16 v[120:123], v[214:217], v[182:185], v[120:123]
	s_waitcnt lgkmcnt(0)
	v_mfma_f32_16x16x32_bf16 v[112:115], v[222:225], v[182:185], v[112:115]
	v_mfma_f32_16x16x32_bf16 v[104:107], v[214:217], v[190:193], v[104:107]
	v_mfma_f32_16x16x32_bf16 v[96:99], v[222:225], v[190:193], v[96:99]
	v_mfma_f32_16x16x32_bf16 v[88:91], v[214:217], v[198:201], v[88:91]
	v_mfma_f32_16x16x32_bf16 v[80:83], v[222:225], v[198:201], v[80:83]
	v_mfma_f32_16x16x32_bf16 v[72:75], v[214:217], v[206:209], v[72:75]
	v_mfma_f32_16x16x32_bf16 v[64:67], v[222:225], v[206:209], v[64:67]
	s_barrier
; template <int N, int K, int EPI>
; __device__ void gemm_phase(const u16* __restrict__ A, const u16* __restrict__ Bt, const EpiArgs ea, char* smem, int tid) {
;     ...
;       if constexpr (EPI == EPI_SWIGLU) {
;         u16* h = ea.o0;
; #pragma unroll
;         for (int ai = 0; ai < 2; ++ai)
; #pragma unroll
;           for (int m = 0; m < 4; ++m) {
;             const int row = brow + ai * HALF + wr * 64 + m * 16 + fr_e;
;             const int col = pn * 128 + wc * 32 + fq_e * 8;
;             u32x4 o;
; #pragma unroll
;             for (int n = 0; n < 2; ++n) {
;               const f32x4 t4 = acc[ai][0][m][n], u4 = acc[ai][1][m][n];
;               f32x2 tl = {t4[0], t4[1]}, th = {t4[2], t4[3]}, ul = {u4[0], u4[1]}, uh = {u4[2], u4[3]};
;               f32x2 el = {__builtin_amdgcn_exp2f(-t4[0]), __builtin_amdgcn_exp2f(-t4[1])};
;               f32x2 eh = {__builtin_amdgcn_exp2f(-t4[2]), __builtin_amdgcn_exp2f(-t4[3])};
;               el = el + 1.f; eh = eh + 1.f;
;               f32x2 rl = {__builtin_amdgcn_rcpf(el[0]), __builtin_amdgcn_rcpf(el[1])};
;               f32x2 rh = {__builtin_amdgcn_rcpf(eh[0]), __builtin_amdgcn_rcpf(eh[1])};
;               const f32x2 hl = tl * ul * rl, hh2 = th * uh * rh;
;               o[2 * n] = pk_bf16(hl[0], hl[1]); o[2 * n + 1] = pk_bf16(hh2[0], hh2[1]);
;             }
;             *(u32x4*)(h + (size_t)row * FF + col) = o;
;           }
	s_or_b32 s70, s70, 64
	s_add_u32 s88, s16, 0x80
	s_addc_u32 s89, s17, 0
	s_add_u32 s16, s16, 0x20080
	s_mov_b32 m0, s31
	s_nop 0
	global_load_lds_dwordx4 v130, s[88:89]
	s_addc_u32 s17, s17, 0
	s_mov_b32 m0, s34
	s_nop 0
	global_load_lds_dwordx4 v130, s[16:17]
	ds_read_b128 v[178:181], v136 offset:49152
	ds_read_b128 v[182:185], v137 offset:49152
	ds_read_b128 v[186:189], v136 offset:51200
	ds_read_b128 v[190:193], v137 offset:51200
	ds_read_b128 v[194:197], v136 offset:53248
	ds_read_b128 v[198:201], v137 offset:53248
	ds_read_b128 v[202:205], v136 offset:55296
	ds_read_b128 v[206:209], v137 offset:55296
	s_add_u32 s16, s18, 0x80
	s_addc_u32 s17, s19, 0
	s_add_u32 s18, s18, 0x20080
	s_mov_b32 m0, s35
	s_nop 0
	global_load_lds_dwordx4 v130, s[16:17]
	s_addc_u32 s19, s19, 0
	s_mov_b32 m0, s36
	s_nop 0
	global_load_lds_dwordx4 v130, s[18:19]
	s_lshl_b64 s[16:17], s[70:71], 1
	s_add_u32 s16, s83, s16
	s_addc_u32 s17, s82, s17
	s_add_u32 s18, s16, 0x20000
	s_mov_b32 m0, s37
	s_nop 0
	global_load_lds_dwordx4 v130, s[16:17]
	s_addc_u32 s19, s17, 0
	s_mov_b32 m0, s42
	s_nop 0
	global_load_lds_dwordx4 v130, s[18:19]
	s_waitcnt vmcnt(8) lgkmcnt(0)
	s_barrier
	s_waitcnt lgkmcnt(7)
	v_mfma_f32_16x16x32_bf16 v[60:63], v[142:145], v[178:181], v[60:63]
	v_mfma_f32_16x16x32_bf16 v[52:55], v[170:173], v[178:181], v[52:55]
	s_waitcnt lgkmcnt(5)
	v_mfma_f32_16x16x32_bf16 v[44:47], v[142:145], v[186:189], v[44:47]
	v_mfma_f32_16x16x32_bf16 v[36:39], v[170:173], v[186:189], v[36:39]
	s_waitcnt lgkmcnt(3)
	v_mfma_f32_16x16x32_bf16 v[28:31], v[142:145], v[194:197], v[28:31]
	v_mfma_f32_16x16x32_bf16 v[20:23], v[170:173], v[194:197], v[20:23]
	s_waitcnt lgkmcnt(1)
	v_mfma_f32_16x16x32_bf16 v[12:15], v[142:145], v[202:205], v[12:15]
	v_mfma_f32_16x16x32_bf16 v[4:7], v[170:173], v[202:205], v[4:7]
	v_mfma_f32_16x16x32_bf16 v[60:63], v[166:169], v[182:185], v[60:63]
	v_mfma_f32_16x16x32_bf16 v[52:55], v[174:177], v[182:185], v[52:55]
	v_mfma_f32_16x16x32_bf16 v[44:47], v[166:169], v[190:193], v[44:47]
	v_mfma_f32_16x16x32_bf16 v[36:39], v[174:177], v[190:193], v[36:39]
	v_mfma_f32_16x16x32_bf16 v[28:31], v[166:169], v[198:201], v[28:31]
	v_mfma_f32_16x16x32_bf16 v[20:23], v[174:177], v[198:201], v[20:23]
	s_waitcnt lgkmcnt(0)
	v_mfma_f32_16x16x32_bf16 v[12:15], v[166:169], v[206:209], v[12:15]
	v_mfma_f32_16x16x32_bf16 v[4:7], v[174:177], v[206:209], v[4:7]
	v_mfma_f32_16x16x32_bf16 v[56:59], v[210:213], v[178:181], v[56:59]
	v_mfma_f32_16x16x32_bf16 v[48:51], v[218:221], v[178:181], v[48:51]
	v_mfma_f32_16x16x32_bf16 v[40:43], v[210:213], v[186:189], v[40:43]
	v_mfma_f32_16x16x32_bf16 v[32:35], v[218:221], v[186:189], v[32:35]
	v_mfma_f32_16x16x32_bf16 v[24:27], v[210:213], v[194:197], v[24:27]
	v_mfma_f32_16x16x32_bf16 v[16:19], v[218:221], v[194:197], v[16:19]
	v_mfma_f32_16x16x32_bf16 v[8:11], v[210:213], v[202:205], v[8:11]
	v_mfma_f32_16x16x32_bf16 v[0:3], v[218:221], v[202:205], v[0:3]
	v_mfma_f32_16x16x32_bf16 v[56:59], v[214:217], v[182:185], v[56:59]
	v_mfma_f32_16x16x32_bf16 v[48:51], v[222:225], v[182:185], v[48:51]
	v_mfma_f32_16x16x32_bf16 v[40:43], v[214:217], v[190:193], v[40:43]
	v_mfma_f32_16x16x32_bf16 v[32:35], v[222:225], v[190:193], v[32:35]
	v_mfma_f32_16x16x32_bf16 v[24:27], v[214:217], v[198:201], v[24:27]
	v_mfma_f32_16x16x32_bf16 v[16:19], v[222:225], v[198:201], v[16:19]
	v_mfma_f32_16x16x32_bf16 v[8:11], v[214:217], v[206:209], v[8:11]
	v_mfma_f32_16x16x32_bf16 v[0:3], v[222:225], v[206:209], v[0:3]
	s_add_i32 s3, s3, 2
	s_addk_i32 s5, 0x80
	s_add_u32 s14, s14, 0x100
	s_addc_u32 s15, s15, 0
	s_cmp_gt_u32 s3, 13
	s_barrier
	s_cbranch_scc0 .LBB0_236
	v_exp_f32_e64 v144, -v124
	v_exp_f32_e64 v145, -v125
	v_exp_f32_e64 v146, -v126
	v_exp_f32_e64 v147, -v127
	v_pk_mul_f32 v[122:123], v[126:127], v[122:123]
	v_pk_add_f32 v[144:145], v[144:145], 1.0 op_sel_hi:[1,0]
	v_pk_mul_f32 v[120:121], v[124:125], v[120:121]
	v_pk_add_f32 v[146:147], v[146:147], 1.0 op_sel_hi:[1,0]
	v_rcp_f32_e32 v144, v144
	v_rcp_f32_e32 v145, v145
	v_rcp_f32_e32 v146, v146
	v_rcp_f32_e32 v147, v147
	v_exp_f32_e64 v124, -v116
	v_exp_f32_e64 v125, -v117
	v_exp_f32_e64 v126, -v118
	v_exp_f32_e64 v127, -v119
	v_pk_mul_f32 v[120:121], v[144:145], v[120:121]
	v_pk_mul_f32 v[122:123], v[146:147], v[122:123]
	v_cvt_pk_bf16_f32 v120, v120, v121
	v_pk_mul_f32 v[114:115], v[118:119], v[114:115]
	v_cvt_pk_bf16_f32 v121, v122, v123
	v_pk_add_f32 v[122:123], v[124:125], 1.0 op_sel_hi:[1,0]
	v_pk_add_f32 v[124:125], v[126:127], 1.0 op_sel_hi:[1,0]
	v_rcp_f32_e32 v122, v122
	v_rcp_f32_e32 v123, v123
	v_rcp_f32_e32 v124, v124
	v_rcp_f32_e32 v125, v125
	v_pk_mul_f32 v[112:113], v[116:117], v[112:113]
	v_pk_mul_f32 v[106:107], v[110:111], v[106:107]
	v_pk_mul_f32 v[112:113], v[122:123], v[112:113]
	v_pk_mul_f32 v[114:115], v[124:125], v[114:115]
	v_cvt_pk_bf16_f32 v122, v112, v113
	v_exp_f32_e64 v112, -v108
	v_cvt_pk_bf16_f32 v123, v114, v115
	v_exp_f32_e64 v113, -v109
	v_exp_f32_e64 v114, -v110
	v_exp_f32_e64 v115, -v111
	v_pk_mul_f32 v[104:105], v[108:109], v[104:105]
	v_pk_add_f32 v[112:113], v[112:113], 1.0 op_sel_hi:[1,0]
	v_exp_f32_e64 v108, -v100
	v_pk_add_f32 v[114:115], v[114:115], 1.0 op_sel_hi:[1,0]
	v_rcp_f32_e32 v112, v112
	v_rcp_f32_e32 v113, v113
	v_rcp_f32_e32 v114, v114
	v_rcp_f32_e32 v115, v115
	v_exp_f32_e64 v109, -v101
	v_exp_f32_e64 v110, -v102
	v_exp_f32_e64 v111, -v103
	v_pk_mul_f32 v[104:105], v[112:113], v[104:105]
	v_pk_mul_f32 v[106:107], v[114:115], v[106:107]
	v_cvt_pk_bf16_f32 v104, v104, v105
	v_pk_mul_f32 v[98:99], v[102:103], v[98:99]
	v_cvt_pk_bf16_f32 v105, v106, v107
	v_pk_add_f32 v[106:107], v[108:109], 1.0 op_sel_hi:[1,0]
; template <int N, int K, int EPI>
; __device__ void gemm_phase(const u16* __restrict__ A, const u16* __restrict__ Bt, const EpiArgs ea, char* smem, int tid) {
;     ...
;       if constexpr (EPI == EPI_SWIGLU) {
;         u16* h = ea.o0;
; #pragma unroll
;         for (int ai = 0; ai < 2; ++ai)
; #pragma unroll
;           for (int m = 0; m < 4; ++m) {
;             const int row = brow + ai * HALF + wr * 64 + m * 16 + fr_e;
;             const int col = pn * 128 + wc * 32 + fq_e * 8;
;             u32x4 o;
; #pragma unroll
;             for (int n = 0; n < 2; ++n) {
;               const f32x4 t4 = acc[ai][0][m][n], u4 = acc[ai][1][m][n];
;               f32x2 tl = {t4[0], t4[1]}, th = {t4[2], t4[3]}, ul = {u4[0], u4[1]}, uh = {u4[2], u4[3]};
;               f32x2 el = {__builtin_amdgcn_exp2f(-t4[0]), __builtin_amdgcn_exp2f(-t4[1])};
;               f32x2 eh = {__builtin_amdgcn_exp2f(-t4[2]), __builtin_amdgcn_exp2f(-t4[3])};
;               el = el + 1.f; eh = eh + 1.f;
;               f32x2 rl = {__builtin_amdgcn_rcpf(el[0]), __builtin_amdgcn_rcpf(el[1])};
;               f32x2 rh = {__builtin_amdgcn_rcpf(eh[0]), __builtin_amdgcn_rcpf(eh[1])};
;               const f32x2 hl = tl * ul * rl, hh2 = th * uh * rh;
;               o[2 * n] = pk_bf16(hl[0], hl[1]); o[2 * n + 1] = pk_bf16(hh2[0], hh2[1]);
;             }
;             *(u32x4*)(h + (size_t)row * FF + col) = o;
;           }
	v_pk_add_f32 v[108:109], v[110:111], 1.0 op_sel_hi:[1,0]
	v_rcp_f32_e32 v106, v106
	v_rcp_f32_e32 v107, v107
	v_rcp_f32_e32 v108, v108
	v_rcp_f32_e32 v109, v109
	v_pk_mul_f32 v[96:97], v[100:101], v[96:97]
	v_pk_mul_f32 v[90:91], v[94:95], v[90:91]
	v_pk_mul_f32 v[96:97], v[106:107], v[96:97]
	v_pk_mul_f32 v[98:99], v[108:109], v[98:99]
	v_cvt_pk_bf16_f32 v106, v96, v97
	v_exp_f32_e64 v96, -v92
	v_cvt_pk_bf16_f32 v107, v98, v99
	v_exp_f32_e64 v97, -v93
	v_exp_f32_e64 v98, -v94
	v_exp_f32_e64 v99, -v95
	v_pk_mul_f32 v[88:89], v[92:93], v[88:89]
	v_pk_add_f32 v[96:97], v[96:97], 1.0 op_sel_hi:[1,0]
	v_exp_f32_e64 v92, -v84
	v_pk_add_f32 v[98:99], v[98:99], 1.0 op_sel_hi:[1,0]
	v_rcp_f32_e32 v96, v96
	v_rcp_f32_e32 v97, v97
	v_rcp_f32_e32 v98, v98
	v_rcp_f32_e32 v99, v99
	v_exp_f32_e64 v93, -v85
	v_exp_f32_e64 v94, -v86
	v_exp_f32_e64 v95, -v87
	v_pk_mul_f32 v[88:89], v[96:97], v[88:89]
	v_pk_mul_f32 v[90:91], v[98:99], v[90:91]
	v_cvt_pk_bf16_f32 v88, v88, v89
	v_pk_mul_f32 v[82:83], v[86:87], v[82:83]
	v_cvt_pk_bf16_f32 v89, v90, v91
	v_pk_add_f32 v[90:91], v[92:93], 1.0 op_sel_hi:[1,0]
	v_pk_add_f32 v[92:93], v[94:95], 1.0 op_sel_hi:[1,0]
	v_rcp_f32_e32 v90, v90
	v_rcp_f32_e32 v91, v91
	v_rcp_f32_e32 v92, v92
	v_rcp_f32_e32 v93, v93
	v_pk_mul_f32 v[80:81], v[84:85], v[80:81]
	v_pk_mul_f32 v[74:75], v[78:79], v[74:75]
	v_pk_mul_f32 v[80:81], v[90:91], v[80:81]
	v_pk_mul_f32 v[82:83], v[92:93], v[82:83]
	v_cvt_pk_bf16_f32 v90, v80, v81
	v_exp_f32_e64 v80, -v76
	v_cvt_pk_bf16_f32 v91, v82, v83
	v_exp_f32_e64 v81, -v77
	v_exp_f32_e64 v82, -v78
	v_exp_f32_e64 v83, -v79
	v_pk_mul_f32 v[72:73], v[76:77], v[72:73]
	v_pk_add_f32 v[80:81], v[80:81], 1.0 op_sel_hi:[1,0]
	v_exp_f32_e64 v76, -v68
	v_pk_add_f32 v[82:83], v[82:83], 1.0 op_sel_hi:[1,0]
	v_rcp_f32_e32 v80, v80
	v_rcp_f32_e32 v81, v81
	v_rcp_f32_e32 v82, v82
	v_rcp_f32_e32 v83, v83
	v_exp_f32_e64 v77, -v69
	v_exp_f32_e64 v78, -v70
	v_exp_f32_e64 v79, -v71
	v_pk_mul_f32 v[72:73], v[80:81], v[72:73]
	v_pk_mul_f32 v[74:75], v[82:83], v[74:75]
	v_cvt_pk_bf16_f32 v72, v72, v73
	s_lshl_b32 s3, s77, 8
	v_cvt_pk_bf16_f32 v73, v74, v75
	v_pk_add_f32 v[74:75], v[76:77], 1.0 op_sel_hi:[1,0]
	v_pk_add_f32 v[76:77], v[78:79], 1.0 op_sel_hi:[1,0]
	v_rcp_f32_e32 v74, v74
	v_rcp_f32_e32 v76, v76
	v_rcp_f32_e32 v77, v77
	v_rcp_f32_e32 v75, v75
	v_mov_b32_e32 v128, v132
	v_mov_b32_e32 v129, v131
	s_add_i32 s3, s3, s43
	v_pk_mul_f32 v[66:67], v[70:71], v[66:67]
	v_add_u32_e32 v142, s3, v129
	s_lshl_b32 s3, s73, 7
	s_or_b32 s3, s3, s66
	v_pk_mul_f32 v[64:65], v[68:69], v[64:65]
	v_pk_mul_f32 v[66:67], v[76:77], v[66:67]
	v_lshl_add_u32 v128, v128, 3, s3
	v_pk_mul_f32 v[64:65], v[74:75], v[64:65]
	v_cvt_pk_bf16_f32 v75, v66, v67
	v_exp_f32_e64 v66, -v60
	v_exp_f32_e64 v67, -v61
	v_exp_f32_e64 v68, -v62
	v_exp_f32_e64 v69, -v63
	v_ashrrev_i32_e32 v129, 31, v128
	v_lshl_add_u64 v[128:129], v[128:129], 1, s[80:81]
	v_cvt_pk_bf16_f32 v74, v64, v65
	v_add_u32_e32 v64, 48, v142
	v_mad_i64_i32 v[64:65], s[10:11], v64, s68, v[128:129]
	global_store_dwordx4 v[64:65], v[72:75], off
	v_pk_add_f32 v[64:65], v[66:67], 1.0 op_sel_hi:[1,0]
	v_pk_add_f32 v[66:67], v[68:69], 1.0 op_sel_hi:[1,0]
	v_rcp_f32_e32 v64, v64
	v_rcp_f32_e32 v65, v65
	v_rcp_f32_e32 v66, v66
	v_rcp_f32_e32 v67, v67
	v_pk_mul_f32 v[58:59], v[62:63], v[58:59]
	v_pk_mul_f32 v[56:57], v[60:61], v[56:57]
	v_exp_f32_e64 v60, -v52
	v_exp_f32_e64 v61, -v53
	v_exp_f32_e64 v62, -v54
	v_exp_f32_e64 v63, -v55
	v_pk_mul_f32 v[56:57], v[64:65], v[56:57]
	v_pk_mul_f32 v[58:59], v[66:67], v[58:59]
	v_cvt_pk_bf16_f32 v56, v56, v57
	v_pk_mul_f32 v[50:51], v[54:55], v[50:51]
	v_cvt_pk_bf16_f32 v57, v58, v59
	v_pk_add_f32 v[58:59], v[60:61], 1.0 op_sel_hi:[1,0]
	v_pk_add_f32 v[60:61], v[62:63], 1.0 op_sel_hi:[1,0]
	v_rcp_f32_e32 v58, v58
	v_rcp_f32_e32 v59, v59
	v_rcp_f32_e32 v60, v60
	v_rcp_f32_e32 v61, v61
	v_pk_mul_f32 v[48:49], v[52:53], v[48:49]
	v_pk_mul_f32 v[42:43], v[46:47], v[42:43]
	v_pk_mul_f32 v[48:49], v[58:59], v[48:49]
	v_pk_mul_f32 v[50:51], v[60:61], v[50:51]
	v_cvt_pk_bf16_f32 v58, v48, v49
	v_exp_f32_e64 v48, -v44
	v_cvt_pk_bf16_f32 v59, v50, v51
	v_exp_f32_e64 v49, -v45
	v_exp_f32_e64 v50, -v46
	v_exp_f32_e64 v51, -v47
	v_pk_mul_f32 v[40:41], v[44:45], v[40:41]
; #define WAIT_V(n) asm volatile("s_waitcnt vmcnt(" #n ")" ::: "memory")
; #define BAR __builtin_amdgcn_s_barrier()
; template <int N, int K, int EPI>
; __device__ void gemm_phase(const u16* __restrict__ A, const u16* __restrict__ Bt, const EpiArgs ea, char* smem, int tid) {
;     ...
;       if constexpr (EPI == EPI_SWIGLU) {
;         u16* h = ea.o0;
; #pragma unroll
;         for (int ai = 0; ai < 2; ++ai)
; #pragma unroll
;           for (int m = 0; m < 4; ++m) {
;             const int row = brow + ai * HALF + wr * 64 + m * 16 + fr_e;
;             const int col = pn * 128 + wc * 32 + fq_e * 8;
;             u32x4 o;
; #pragma unroll
;             for (int n = 0; n < 2; ++n) {
;               const f32x4 t4 = acc[ai][0][m][n], u4 = acc[ai][1][m][n];
;               f32x2 tl = {t4[0], t4[1]}, th = {t4[2], t4[3]}, ul = {u4[0], u4[1]}, uh = {u4[2], u4[3]};
;               f32x2 el = {__builtin_amdgcn_exp2f(-t4[0]), __builtin_amdgcn_exp2f(-t4[1])};
;               f32x2 eh = {__builtin_amdgcn_exp2f(-t4[2]), __builtin_amdgcn_exp2f(-t4[3])};
;               el = el + 1.f; eh = eh + 1.f;
;               f32x2 rl = {__builtin_amdgcn_rcpf(el[0]), __builtin_amdgcn_rcpf(el[1])};
;               f32x2 rh = {__builtin_amdgcn_rcpf(eh[0]), __builtin_amdgcn_rcpf(eh[1])};
;               const f32x2 hl = tl * ul * rl, hh2 = th * uh * rh;
;               o[2 * n] = pk_bf16(hl[0], hl[1]); o[2 * n + 1] = pk_bf16(hh2[0], hh2[1]);
;             }
;             *(u32x4*)(h + (size_t)row * FF + col) = o;
;           }
;     ...
;     if (!has_next) break;
; #pragma unroll
;     for (int ai = 0; ai < 2; ++ai)
; #pragma unroll
;       for (int bj = 0; bj < 2; ++bj)
; #pragma unroll
;         for (int m = 0; m < 4; ++m)
; #pragma unroll
;           for (int n = 0; n < 2; ++n) acc[ai][bj][m][n] = f32x4{0.f, 0.f, 0.f, 0.f};
;     v = vn; pm = pmn; pn = pnn; Ab = Abn; Bb = Bbn;
;   }
;   WAIT_V(0);
;   if (wr == 0) BAR;
	v_pk_add_f32 v[48:49], v[48:49], 1.0 op_sel_hi:[1,0]
	v_exp_f32_e64 v44, -v36
	v_pk_add_f32 v[50:51], v[50:51], 1.0 op_sel_hi:[1,0]
	v_rcp_f32_e32 v48, v48
	v_rcp_f32_e32 v49, v49
	v_rcp_f32_e32 v50, v50
	v_rcp_f32_e32 v51, v51
	v_exp_f32_e64 v45, -v37
	v_exp_f32_e64 v46, -v38
	v_exp_f32_e64 v47, -v39
	v_pk_mul_f32 v[40:41], v[48:49], v[40:41]
	v_pk_mul_f32 v[42:43], v[50:51], v[42:43]
	v_cvt_pk_bf16_f32 v40, v40, v41
	v_pk_mul_f32 v[34:35], v[38:39], v[34:35]
	v_cvt_pk_bf16_f32 v41, v42, v43
	v_pk_add_f32 v[42:43], v[44:45], 1.0 op_sel_hi:[1,0]
	v_pk_add_f32 v[44:45], v[46:47], 1.0 op_sel_hi:[1,0]
	v_rcp_f32_e32 v42, v42
	v_rcp_f32_e32 v43, v43
	v_rcp_f32_e32 v44, v44
	v_rcp_f32_e32 v45, v45
	v_pk_mul_f32 v[32:33], v[36:37], v[32:33]
	v_pk_mul_f32 v[26:27], v[30:31], v[26:27]
	v_pk_mul_f32 v[32:33], v[42:43], v[32:33]
	v_pk_mul_f32 v[34:35], v[44:45], v[34:35]
	v_cvt_pk_bf16_f32 v42, v32, v33
	v_exp_f32_e64 v32, -v28
	v_cvt_pk_bf16_f32 v43, v34, v35
	v_exp_f32_e64 v33, -v29
	v_exp_f32_e64 v34, -v30
	v_exp_f32_e64 v35, -v31
	v_pk_mul_f32 v[24:25], v[28:29], v[24:25]
	v_pk_add_f32 v[32:33], v[32:33], 1.0 op_sel_hi:[1,0]
	v_exp_f32_e64 v28, -v20
	v_pk_add_f32 v[34:35], v[34:35], 1.0 op_sel_hi:[1,0]
	v_rcp_f32_e32 v32, v32
	v_rcp_f32_e32 v33, v33
	v_rcp_f32_e32 v34, v34
	v_rcp_f32_e32 v35, v35
	v_exp_f32_e64 v29, -v21
	v_exp_f32_e64 v30, -v22
	v_exp_f32_e64 v31, -v23
	v_pk_mul_f32 v[24:25], v[32:33], v[24:25]
	v_pk_mul_f32 v[26:27], v[34:35], v[26:27]
	v_cvt_pk_bf16_f32 v24, v24, v25
	v_pk_mul_f32 v[18:19], v[22:23], v[18:19]
	v_cvt_pk_bf16_f32 v25, v26, v27
	v_pk_add_f32 v[26:27], v[28:29], 1.0 op_sel_hi:[1,0]
	v_pk_add_f32 v[28:29], v[30:31], 1.0 op_sel_hi:[1,0]
	v_rcp_f32_e32 v26, v26
	v_rcp_f32_e32 v27, v27
	v_rcp_f32_e32 v28, v28
	v_rcp_f32_e32 v29, v29
	v_pk_mul_f32 v[16:17], v[20:21], v[16:17]
	v_pk_mul_f32 v[8:9], v[12:13], v[8:9]
	v_pk_mul_f32 v[16:17], v[26:27], v[16:17]
	v_pk_mul_f32 v[18:19], v[28:29], v[18:19]
	v_cvt_pk_bf16_f32 v26, v16, v17
	v_exp_f32_e64 v16, -v12
	v_cvt_pk_bf16_f32 v27, v18, v19
	v_exp_f32_e64 v17, -v13
	v_exp_f32_e64 v18, -v14
	v_exp_f32_e64 v19, -v15
	v_exp_f32_e64 v12, -v4
	v_pk_add_f32 v[16:17], v[16:17], 1.0 op_sel_hi:[1,0]
	v_exp_f32_e64 v13, -v5
	v_pk_add_f32 v[18:19], v[18:19], 1.0 op_sel_hi:[1,0]
	v_rcp_f32_e32 v16, v16
	v_rcp_f32_e32 v17, v17
	v_rcp_f32_e32 v18, v18
	v_rcp_f32_e32 v19, v19
	v_pk_mul_f32 v[10:11], v[14:15], v[10:11]
	v_pk_mul_f32 v[8:9], v[16:17], v[8:9]
	v_exp_f32_e64 v14, -v6
	v_pk_mul_f32 v[10:11], v[18:19], v[10:11]
	v_exp_f32_e64 v15, -v7
	v_cvt_pk_bf16_f32 v8, v8, v9
	v_cvt_pk_bf16_f32 v9, v10, v11
	v_pk_add_f32 v[10:11], v[12:13], 1.0 op_sel_hi:[1,0]
	v_pk_add_f32 v[12:13], v[14:15], 1.0 op_sel_hi:[1,0]
	v_rcp_f32_e32 v10, v10
	v_rcp_f32_e32 v11, v11
	v_pk_mul_f32 v[0:1], v[4:5], v[0:1]
	v_rcp_f32_e32 v12, v12
	v_rcp_f32_e32 v13, v13
	v_pk_mul_f32 v[0:1], v[10:11], v[0:1]
	v_add_u32_e32 v100, 16, v142
	v_add_u32_e32 v84, 32, v142
	v_add_u32_e32 v70, 0x80, v142
	v_add_u32_e32 v36, 0x90, v142
	v_add_u32_e32 v20, 0xa0, v142
	v_cvt_pk_bf16_f32 v10, v0, v1
	v_add_u32_e32 v0, 0xb0, v142
	v_mad_i64_i32 v[116:117], s[10:11], v142, s68, v[128:129]
	v_mad_i64_i32 v[100:101], s[10:11], v100, s68, v[128:129]
	v_mad_i64_i32 v[84:85], s[10:11], v84, s68, v[128:129]
	v_mad_i64_i32 v[52:53], s[10:11], v70, s68, v[128:129]
	v_mad_i64_i32 v[36:37], s[10:11], v36, s68, v[128:129]
	v_mad_i64_i32 v[20:21], s[10:11], v20, s68, v[128:129]
	v_mad_i64_i32 v[0:1], s[10:11], v0, s68, v[128:129]
	v_pk_mul_f32 v[2:3], v[6:7], v[2:3]
	s_and_b64 vcc, exec, s[0:1]
	s_mov_b32 s77, s2
	s_mov_b32 s73, s4
	s_mov_b64 s[12:13], s[8:9]
	s_mov_b64 s[10:11], s[6:7]
	global_store_dwordx4 v[116:117], v[120:123], off
	global_store_dwordx4 v[100:101], v[104:107], off
	global_store_dwordx4 v[84:85], v[88:91], off
	global_store_dwordx4 v[52:53], v[56:59], off
	global_store_dwordx4 v[36:37], v[40:43], off
	global_store_dwordx4 v[20:21], v[24:27], off
	v_pk_mul_f32 v[2:3], v[12:13], v[2:3]
	s_nop 0
	v_cvt_pk_bf16_f32 v11, v2, v3
	global_store_dwordx4 v[0:1], v[8:11], off
	s_cbranch_vccz .LBB0_233
	s_setprio 0
	s_waitcnt vmcnt(0)
	v_readlane_b32 s36, v226, 30
	s_cmpk_gt_u32 s22, 0xff
	s_mov_b64 s[34:35], s[96:97]
	v_readlane_b32 s37, v226, 31
	s_cbranch_scc1 .LBB0_240
	s_barrier
